# differential attention QK^T: all K fragment reads of a tile issued up front into spare registers (prefetch depth 4)
# baseline (speedup 1.0000x reference)
; __device__ __forceinline__ int opaque_tid() { int t = threadIdx.x; asm volatile("" : "+v"(t)); return t; }
; __device__ __forceinline__ int crow(int r, int hi) { return (r & 3) + 8 * (r >> 2) + 4 * hi; }
; template <int DK, bool NA, bool QL, int SD> ...
;     ...
;   if (hi == 0) li_l[r32] = l_reg; asm volatile("s_waitcnt vmcnt(0) lgkmcnt(0)" ::: "memory");
; #pragma unroll
;   for (int r = 0; r < 16; ++r) { const float rl = __builtin_amdgcn_rcpf(li_l[crow(r, hi)]);
; #pragma unroll
;     for (int d = 0; d < 4; ++d) o[d][r] *= rl; }
; __global__ void __launch_bounds__(NTHR) mega_fwd(Params p) {
;     ...
;                     { const int t3 = opaque_tid(), l3 = t3 & 63, r32 = l3 & 31; const v4u* STv = (const v4u*)((char*)lds + 69632) + t3;
;                       const float* sg = p.diff_subln + l * 128;
;                       float gsub[4], ss[16];
; #pragma unroll
;                       for (int d = 0; d < 4; ++d) gsub[d] = sg[32 * d + r32] * (1.0f - lam_init);
; #pragma unroll
;                       for (int r = 0; r < 16; ++r) ss[r] = 0.f;
; #pragma unroll
;                       for (int k = 0; k < 8; ++k) { const int d = k >> 1, r0 = 8 * (k & 1); const v4u w = STv[k * 512];
; #pragma unroll
;                           for (int i = 0; i < 4; ++i) { const unsigned wi = i == 0 ? w.x : (i == 1 ? w.y : (i == 2 ? w.z : w.w));
;                               const float va = bf2f((unsigned short)(wi & 0xffffu)) - lam * o[d][r0 + 2 * i], vb = bf2f((unsigned short)(wi >> 16)) - lam * o[d][r0 + 2 * i + 1];
;                               o[d][r0 + 2 * i] = va; o[d][r0 + 2 * i + 1] = vb; ss[r0 + 2 * i] += va * va; ss[r0 + 2 * i + 1] += vb * vb; } }
.LBB0_368:
	s_or_b64 exec, exec, s[2:3]
	v_mov_b32_e32 v190, 0x260
	v_mov_b32_e32 v191, 1
	v_mbcnt_lo_u32_b32 v192, -1, 0
	v_mbcnt_hi_u32_b32 v192, -1, v192
	v_mov_b32_e32 v193, 0x3a83126f
	v_mov_b64_e32 v[168:169], 0x100
	v_mov_b64_e32 v[170:171], 0xff
	v_mov_b32_e32 v194, 0x3c23d70a
	v_mov_b32_e32 v195, 0x2800
	v_mov_b64_e32 v[196:197], 0x580
	v_mov_b32_e32 v194, 0x3c23d70a
	v_mov_b32_e32 v195, 0x2800
	v_mov_b64_e32 v[196:197], 0x580
	s_waitcnt vmcnt(0) lgkmcnt(0)
	v_add_u32_e32 v0, v207, v0
	ds_read_b128 v[72:75], v0
	ds_read_b128 v[76:79], v0 offset:32
	v_readlane_b32 s0, v255, 40
	v_readlane_b32 s1, v255, 41
	s_mov_b32 s2, 0xf800000
	s_waitcnt lgkmcnt(1)
	v_rcp_f32_e32 v67, v72
	v_rcp_f32_e32 v68, v73
	v_mul_f32_e32 v70, v67, v34
	v_mul_f32_e32 v34, v67, v18
	v_rcp_f32_e32 v18, v74
	v_mul_f32_e32 v69, v67, v50
	v_mul_f32_e32 v71, v68, v35
	v_mul_f32_e32 v66, v68, v19
	v_mul_f32_e32 v50, v18, v4
	v_rcp_f32_e32 v4, v75
	v_mul_f32_e32 v72, v18, v52
	v_mul_f32_e32 v73, v18, v36
	v_mul_f32_e32 v36, v18, v20
	v_mul_f32_e32 v82, v4, v5
	v_mul_f32_e32 v74, v4, v53
	v_mul_f32_e32 v53, v4, v37
	v_mul_f32_e32 v52, v4, v21
	s_waitcnt lgkmcnt(0)
	v_rcp_f32_e32 v4, v76
	v_mul_f32_e32 v2, v67, v2
	v_mul_f32_e32 v3, v68, v3
	v_mul_f32_e32 v51, v68, v51
	v_mul_f32_e32 v37, v4, v6
	v_mul_f32_e32 v80, v4, v54
	v_mul_f32_e32 v76, v4, v38
	v_mul_f32_e32 v75, v4, v22
	v_rcp_f32_e32 v4, v77
	s_nop 0
	v_mul_f32_e32 v54, v4, v7
	v_mul_f32_e32 v38, v4, v55
	v_mul_f32_e32 v81, v4, v39
	v_mul_f32_e32 v77, v4, v23
	v_rcp_f32_e32 v4, v78
	ds_read_b128 v[20:23], v0 offset:64
	v_mul_f32_e32 v55, v4, v8
	v_mul_f32_e32 v88, v4, v56
	v_mul_f32_e32 v84, v4, v40
	v_mul_f32_e32 v40, v4, v24
	v_rcp_f32_e32 v4, v79
	s_nop 0
	v_mul_f32_e32 v86, v4, v9
	v_mul_f32_e32 v57, v4, v57
	v_mul_f32_e32 v85, v4, v41
	v_mul_f32_e32 v41, v4, v25
	s_waitcnt lgkmcnt(0)
	v_rcp_f32_e32 v4, v20
	s_nop 0
	v_mul_f32_e32 v7, v4, v10
	v_mul_f32_e32 v8, v4, v58
	v_mul_f32_e32 v10, v4, v42
	v_mul_f32_e32 v18, v4, v26
	v_rcp_f32_e32 v4, v21
	s_nop 0
	v_mul_f32_e32 v9, v4, v11
	v_mul_f32_e32 v21, v4, v59
	v_mul_f32_e32 v35, v4, v43
	v_mul_f32_e32 v20, v4, v27
	v_rcp_f32_e32 v4, v22
	s_nop 0
	v_mul_f32_e32 v12, v4, v12
	v_mul_f32_e32 v11, v4, v60
	v_mul_f32_e32 v25, v4, v44
	v_mul_f32_e32 v22, v4, v28
	v_rcp_f32_e32 v4, v23
	s_nop 0
	v_mul_f32_e32 v28, v4, v45
	ds_read_b128 v[42:45], v0 offset:96
	v_mul_f32_e32 v19, v4, v13
	v_mul_f32_e32 v27, v4, v61
	v_mul_f32_e32 v23, v4, v29
	s_waitcnt lgkmcnt(0)
	v_rcp_f32_e32 v0, v42
	s_nop 0
	v_mul_f32_e32 v42, v0, v14
	v_mul_f32_e32 v13, v0, v62
	v_mul_f32_e32 v46, v0, v46
	v_mul_f32_e32 v14, v0, v30
	v_rcp_f32_e32 v0, v43
	s_nop 0
	v_mul_f32_e32 v30, v0, v15
	v_mul_f32_e32 v61, v0, v63
	v_mul_f32_e32 v78, v0, v47
	v_mul_f32_e32 v24, v0, v31
	v_rcp_f32_e32 v0, v44
	v_mov_b32_e32 v15, v188
	v_mul_f32_e32 v16, v0, v16
	v_mul_f32_e32 v43, v0, v64
	v_mul_f32_e32 v56, v0, v48
	v_mul_f32_e32 v31, v0, v32
	v_rcp_f32_e32 v0, v45
	s_nop 0
	v_mul_f32_e32 v45, v0, v17
	v_mul_f32_e32 v17, v0, v65
	v_mul_f32_e32 v79, v0, v49
	v_mul_f32_e32 v32, v0, v33
	v_and_b32_e32 v0, 31, v15
	v_lshl_add_u32 v15, v15, 4, 0
	v_add_u32_e32 v92, 0x11000, v15
	ds_read_b128 v[62:65], v92
	ds_read_b128 v[94:97], v92 offset:8192
	v_lshlrev_b32_e32 v6, 2, v0
	global_load_dword v0, v6, s[0:1]
	global_load_dword v4, v6, s[0:1] offset:128
	global_load_dword v5, v6, s[0:1] offset:256
	s_waitcnt lgkmcnt(1)
	v_lshlrev_b32_e32 v15, 16, v62
	v_fma_f32 v87, -v202, v2, v15
	v_and_b32_e32 v2, 0xffff0000, v62
	v_fma_f32 v33, -v202, v3, v2
	v_lshlrev_b32_e32 v2, 16, v63
	v_fma_f32 v39, -v202, v50, v2
	v_and_b32_e32 v2, 0xffff0000, v63
	v_fma_f32 v49, -v202, v82, v2
	v_lshlrev_b32_e32 v2, 16, v64
	v_fma_f32 v58, -v202, v37, v2
	v_and_b32_e32 v2, 0xffff0000, v64
	v_fma_f32 v67, -v202, v54, v2
	v_lshlrev_b32_e32 v2, 16, v65
	v_fma_f32 v64, -v202, v55, v2
	v_and_b32_e32 v2, 0xffff0000, v65
	v_fma_f32 v54, -v202, v86, v2
	s_waitcnt lgkmcnt(0)
	v_lshlrev_b32_e32 v2, 16, v94
	v_fma_f32 v47, -v202, v7, v2
	v_and_b32_e32 v2, 0xffff0000, v94
	v_fma_f32 v37, -v202, v9, v2
	v_lshlrev_b32_e32 v2, 16, v95
	v_fma_f32 v29, -v202, v12, v2
	v_and_b32_e32 v2, 0xffff0000, v95
	v_fma_f32 v19, -v202, v19, v2
	v_lshlrev_b32_e32 v2, 16, v96
	v_fma_f32 v15, -v202, v42, v2
	v_and_b32_e32 v2, 0xffff0000, v96
	v_fma_f32 v9, -v202, v30, v2
	v_lshlrev_b32_e32 v2, 16, v97
	v_fma_f32 v7, -v202, v16, v2
	v_and_b32_e32 v2, 0xffff0000, v97
	ds_read_b128 v[94:97], v92 offset:16384
	global_load_dword v6, v6, s[0:1] offset:384
	v_mul_f32_e32 v83, v33, v33
	v_mul_f32_e32 v50, v49, v49
	v_mul_f32_e32 v68, v67, v67
	s_waitcnt lgkmcnt(0)
	v_lshlrev_b32_e32 v16, 16, v94
	v_fma_f32 v89, -v202, v69, v16
	v_and_b32_e32 v16, 0xffff0000, v94
	v_fma_f32 v86, -v202, v51, v16
	v_lshlrev_b32_e32 v16, 16, v95
	v_fma_f32 v42, -v202, v72, v16
	v_and_b32_e32 v16, 0xffff0000, v95
	v_fma_f32 v51, -v202, v74, v16
	v_lshlrev_b32_e32 v16, 16, v96
	v_fma_f32 v59, -v202, v80, v16
	v_and_b32_e32 v16, 0xffff0000, v96
	v_fma_f32 v69, -v202, v38, v16
	v_lshlrev_b32_e32 v16, 16, v97
	v_fma_f32 v72, -v202, v88, v16
	v_and_b32_e32 v16, 0xffff0000, v97
	ds_read_b128 v[94:97], v92 offset:24576
	v_fma_f32 v63, -v202, v57, v16
	v_mul_f32_e32 v91, v89, v89
	v_fmac_f32_e32 v91, v87, v87
	v_fmac_f32_e32 v83, v86, v86
	s_waitcnt lgkmcnt(0)
	v_lshlrev_b32_e32 v16, 16, v94
	v_fma_f32 v57, -v202, v8, v16
	v_and_b32_e32 v8, 0xffff0000, v94
	v_fma_f32 v48, -v202, v21, v8
	v_lshlrev_b32_e32 v8, 16, v95
	v_fma_f32 v38, -v202, v11, v8
	v_and_b32_e32 v8, 0xffff0000, v95
	v_fma_f32 v30, -v202, v27, v8
	v_lshlrev_b32_e32 v8, 16, v96
	v_fma_f32 v21, -v202, v13, v8
	v_and_b32_e32 v8, 0xffff0000, v96
	v_fma_f32 v16, -v202, v61, v8
	v_lshlrev_b32_e32 v8, 16, v97
	v_fma_f32 v11, -v202, v43, v8
	v_and_b32_e32 v8, 0xffff0000, v97
	ds_read_b128 v[94:97], v92 offset:32768
	v_fma_f32 v8, -v202, v17, v8
	v_mul_f32_e32 v82, v42, v42
	v_fmac_f32_e32 v82, v39, v39
	v_fmac_f32_e32 v50, v51, v51
	s_waitcnt lgkmcnt(0)
; __global__ void __launch_bounds__(NTHR) mega_fwd(Params p) {
;     ...
;                       for (int k = 0; k < 8; ++k) { const int d = k >> 1, r0 = 8 * (k & 1); const v4u w = STv[k * 512];
; #pragma unroll
;                           for (int i = 0; i < 4; ++i) { const unsigned wi = i == 0 ? w.x : (i == 1 ? w.y : (i == 2 ? w.z : w.w));
;                               const float va = bf2f((unsigned short)(wi & 0xffffu)) - lam * o[d][r0 + 2 * i], vb = bf2f((unsigned short)(wi >> 16)) - lam * o[d][r0 + 2 * i + 1];
;                               o[d][r0 + 2 * i] = va; o[d][r0 + 2 * i + 1] = vb; ss[r0 + 2 * i] += va * va; ss[r0 + 2 * i + 1] += vb * vb; } }
; #pragma unroll
;                       for (int r = 0; r < 16; ++r) { float q = ss[r]; q += __shfl_xor(q, 1); q += __shfl_xor(q, 2); q += __shfl_xor(q, 4); q += __shfl_xor(q, 8); q += __shfl_xor(q, 16);
;                           const float rstd = 1.0f / sqrtf(q * (1.0f / 128.0f) + EPS);
; #pragma unroll
;                           for (int d = 0; d < 4; ++d) o[d][r] *= rstd * gsub[d]; } }
	v_lshlrev_b32_e32 v17, 16, v94
	v_fma_f32 v93, -v202, v70, v17
	v_and_b32_e32 v17, 0xffff0000, v94
	v_fma_f32 v90, -v202, v71, v17
	v_lshlrev_b32_e32 v17, 16, v95
	v_fma_f32 v88, -v202, v73, v17
	v_and_b32_e32 v17, 0xffff0000, v95
	v_fma_f32 v80, -v202, v53, v17
	v_lshlrev_b32_e32 v17, 16, v96
	v_fma_f32 v61, -v202, v76, v17
	v_and_b32_e32 v17, 0xffff0000, v96
	v_fma_f32 v70, -v202, v81, v17
	v_lshlrev_b32_e32 v17, 16, v97
	v_fma_f32 v76, -v202, v84, v17
	v_and_b32_e32 v17, 0xffff0000, v97
	ds_read_b128 v[94:97], v92 offset:40960
	v_fma_f32 v73, -v202, v85, v17
	v_fmac_f32_e32 v91, v93, v93
	v_fmac_f32_e32 v83, v90, v90
	s_waitcnt vmcnt(3)
	v_mul_f32_e32 v0, v201, v0
	s_waitcnt lgkmcnt(0)
	v_lshlrev_b32_e32 v17, 16, v94
	v_fma_f32 v71, -v202, v10, v17
	v_and_b32_e32 v10, 0xffff0000, v94
	v_fma_f32 v62, -v202, v35, v10
	v_lshlrev_b32_e32 v10, 16, v95
	v_fma_f32 v53, -v202, v25, v10
	v_and_b32_e32 v10, 0xffff0000, v95
	v_fma_f32 v43, -v202, v28, v10
	v_lshlrev_b32_e32 v10, 16, v96
	v_fma_f32 v35, -v202, v46, v10
	v_and_b32_e32 v10, 0xffff0000, v96
	v_fma_f32 v25, -v202, v78, v10
	v_lshlrev_b32_e32 v10, 16, v97
	v_fma_f32 v17, -v202, v56, v10
	v_and_b32_e32 v10, 0xffff0000, v97
	ds_read_b128 v[94:97], v92 offset:49152
	v_fma_f32 v10, -v202, v79, v10
	s_waitcnt vmcnt(2)
	v_mul_f32_e32 v4, v201, v4
	s_waitcnt vmcnt(1)
	v_mul_f32_e32 v5, v201, v5
	s_waitcnt vmcnt(0)
	v_mul_f32_e32 v6, v201, v6
	s_waitcnt lgkmcnt(0)
	v_lshlrev_b32_e32 v28, 16, v94
	v_fma_f32 v85, -v202, v34, v28
	v_and_b32_e32 v28, 0xffff0000, v94
	v_fma_f32 v34, -v202, v66, v28
	v_lshlrev_b32_e32 v28, 16, v95
	v_fma_f32 v84, -v202, v36, v28
	v_and_b32_e32 v28, 0xffff0000, v95
	v_fma_f32 v52, -v202, v52, v28
	v_lshlrev_b32_e32 v28, 16, v96
	v_fma_f32 v81, -v202, v75, v28
	v_and_b32_e32 v28, 0xffff0000, v96
	v_fma_f32 v79, -v202, v77, v28
	v_lshlrev_b32_e32 v28, 16, v97
	v_fma_f32 v78, -v202, v40, v28
	v_and_b32_e32 v28, 0xffff0000, v97
	ds_read_b128 v[94:97], v92 offset:57344
	v_fma_f32 v77, -v202, v41, v28
	v_fmac_f32_e32 v91, v85, v85
	v_fmac_f32_e32 v83, v34, v34
	v_fmac_f32_e32 v82, v88, v88
	s_waitcnt lgkmcnt(0)
	v_lshlrev_b32_e32 v28, 16, v94
	v_fma_f32 v75, -v202, v18, v28
	v_and_b32_e32 v18, 0xffff0000, v94
	v_fma_f32 v66, -v202, v20, v18
	s_nop 1
	v_mov_b32_dpp v20, v91 quad_perm:[1,0,3,2] row_mask:0xf bank_mask:0xf
	v_lshlrev_b32_e32 v18, 16, v95
	v_fma_f32 v56, -v202, v22, v18
	v_and_b32_e32 v18, 0xffff0000, v95
	v_fma_f32 v46, -v202, v23, v18
	s_waitcnt lgkmcnt(0)
	v_add_f32_e32 v20, v91, v20
	s_nop 1
	v_mov_b32_dpp v22, v20 quad_perm:[2,3,0,1] row_mask:0xf bank_mask:0xf
	v_lshlrev_b32_e32 v18, 16, v96
	v_fma_f32 v36, -v202, v14, v18
	v_and_b32_e32 v14, 0xffff0000, v96
	v_fma_f32 v28, -v202, v24, v14
	s_waitcnt lgkmcnt(0)
	v_add_f32_e32 v20, v20, v22
	s_nop 1
	v_mov_b32_dpp v22, v20 row_half_mirror row_mask:0xf bank_mask:0xf
	v_lshlrev_b32_e32 v14, 16, v97
	v_fma_f32 v18, -v202, v31, v14
	v_and_b32_e32 v14, 0xffff0000, v97
	v_fma_f32 v14, -v202, v32, v14
	s_waitcnt lgkmcnt(0)
	v_add_f32_e32 v20, v20, v22
	s_nop 1
	v_mov_b32_dpp v22, v20 row_mirror row_mask:0xf bank_mask:0xf
	v_fmac_f32_e32 v82, v84, v84
	v_fmac_f32_e32 v50, v80, v80
	v_fmac_f32_e32 v50, v52, v52
	v_mul_f32_e32 v60, v59, v59
	s_waitcnt lgkmcnt(0)
	v_add_f32_e32 v20, v20, v22
	v_mov_b32_e32 v22, v20
	s_nop 1
	v_permlane16_swap_b32_e32 v20, v22
	v_fmac_f32_e32 v60, v58, v58
	v_fmac_f32_e32 v60, v61, v61
	v_fmac_f32_e32 v60, v81, v81
	v_fmac_f32_e32 v68, v69, v69
	s_waitcnt lgkmcnt(0)
	v_add_f32_e32 v20, v20, v22
	v_fmamk_f32 v20, v20, 0x3c000000, v189
	v_cmp_gt_f32_e32 vcc, s2, v20
	v_mul_f32_e32 v22, 0x4f800000, v20
	v_fmac_f32_e32 v68, v70, v70
	v_cndmask_b32_e32 v20, v20, v22, vcc
	v_sqrt_f32_e32 v22, v20
	v_fmac_f32_e32 v68, v79, v79
	v_mul_f32_e32 v74, v72, v72
	v_fmac_f32_e32 v74, v64, v64
	v_add_u32_e32 v23, -1, v22
	v_fma_f32 v24, -v23, v22, v20
	v_cmp_ge_f32_e64 s[0:1], 0, v24
	v_add_u32_e32 v24, 1, v22
	v_fmac_f32_e32 v74, v76, v76
	v_cndmask_b32_e64 v23, v22, v23, s[0:1]
	v_fma_f32 v22, -v24, v22, v20
	v_cmp_lt_f32_e64 s[0:1], 0, v22
	v_fmac_f32_e32 v74, v78, v78
	v_mul_f32_e32 v55, v54, v54
	v_cndmask_b32_e64 v22, v23, v24, s[0:1]
	v_mul_f32_e32 v23, 0x37800000, v22
	v_cndmask_b32_e32 v22, v22, v23, vcc
	v_cmp_class_f32_e32 vcc, v20, v190
	v_fmac_f32_e32 v55, v63, v63
	v_fmac_f32_e32 v55, v73, v73
	v_cndmask_b32_e32 v20, v22, v20, vcc
	v_div_scale_f32 v22, s[0:1], v20, v20, 1.0
	v_rcp_f32_e32 v23, v22
	v_fmac_f32_e32 v55, v77, v77
	v_mul_f32_e32 v65, v57, v57
	v_fmac_f32_e32 v65, v47, v47
	v_fma_f32 v24, -v22, v23, 1.0
	v_fmac_f32_e32 v23, v24, v23
	v_div_scale_f32 v24, vcc, 1.0, v20, 1.0
	v_mul_f32_e32 v31, v24, v23
	v_fma_f32 v32, -v22, v31, v24
	v_fmac_f32_e32 v31, v32, v23
	v_fma_f32 v22, -v22, v31, v24
	v_div_fmas_f32 v22, v22, v23, v31
	s_nop 1
	v_mov_b32_dpp v31, v83 quad_perm:[1,0,3,2] row_mask:0xf bank_mask:0xf
	v_div_fixup_f32 v24, v22, v20, 1.0
	v_mul_f32_e32 v20, v24, v0
	v_mul_f32_e32 v22, v24, v4
	v_mul_f32_e32 v23, v24, v5
	s_waitcnt lgkmcnt(0)
	v_add_f32_e32 v31, v83, v31
	s_nop 1
	v_mov_b32_dpp v32, v31 quad_perm:[2,3,0,1] row_mask:0xf bank_mask:0xf
	v_mul_f32_e32 v24, v24, v6
	v_mul_f32_e32 v24, v24, v85
	v_fmac_f32_e32 v65, v71, v71
	v_fmac_f32_e32 v65, v75, v75
	s_waitcnt lgkmcnt(0)
	v_add_f32_e32 v31, v31, v32
	s_nop 1
	v_mov_b32_dpp v32, v31 row_half_mirror row_mask:0xf bank_mask:0xf
	v_mul_f32_e32 v44, v37, v37
	v_fmac_f32_e32 v44, v48, v48
	v_fmac_f32_e32 v44, v62, v62
	v_fmac_f32_e32 v44, v66, v66
	s_waitcnt lgkmcnt(0)
	v_add_f32_e32 v31, v31, v32
	s_nop 1
	v_mov_b32_dpp v32, v31 row_mirror row_mask:0xf bank_mask:0xf
	v_fma_f32 v2, -v202, v45, v2
	v_mul_f32_e32 v45, v38, v38
	v_fmac_f32_e32 v45, v29, v29
	v_fmac_f32_e32 v45, v53, v53
	s_waitcnt lgkmcnt(0)
; __global__ void __launch_bounds__(NTHR) mega_fwd(Params p) {
;     ...
; #pragma unroll
;                       for (int r = 0; r < 16; ++r) { float q = ss[r]; q += __shfl_xor(q, 1); q += __shfl_xor(q, 2); q += __shfl_xor(q, 4); q += __shfl_xor(q, 8); q += __shfl_xor(q, 16);
;                           const float rstd = 1.0f / sqrtf(q * (1.0f / 128.0f) + EPS);
; #pragma unroll
;                           for (int d = 0; d < 4; ++d) o[d][r] *= rstd * gsub[d]; } }
	v_add_f32_e32 v31, v31, v32
	v_mov_b32_e32 v32, v31
	s_nop 1
	v_permlane16_swap_b32_e32 v31, v32
	v_fmac_f32_e32 v45, v56, v56
	v_mul_f32_e32 v26, v19, v19
	v_fmac_f32_e32 v26, v30, v30
	v_fmac_f32_e32 v26, v43, v43
	s_waitcnt lgkmcnt(0)
	v_add_f32_e32 v31, v31, v32
	v_fmamk_f32 v31, v31, 0x3c000000, v189
	v_cmp_gt_f32_e32 vcc, s2, v31
	v_mul_f32_e32 v32, 0x4f800000, v31
	v_fmac_f32_e32 v26, v46, v46
	v_cndmask_b32_e32 v31, v31, v32, vcc
	v_sqrt_f32_e32 v32, v31
	v_mul_f32_e32 v27, v21, v21
	v_fmac_f32_e32 v27, v15, v15
	v_fmac_f32_e32 v27, v35, v35
	v_add_u32_e32 v40, -1, v32
	v_fma_f32 v41, -v40, v32, v31
	v_cmp_ge_f32_e64 s[0:1], 0, v41
	v_add_u32_e32 v41, 1, v32
	v_fmac_f32_e32 v27, v36, v36
	v_cndmask_b32_e64 v40, v32, v40, s[0:1]
	v_fma_f32 v32, -v41, v32, v31
	v_cmp_lt_f32_e64 s[0:1], 0, v32
	v_mul_f32_e32 v12, v9, v9
	v_fmac_f32_e32 v12, v16, v16
	v_cndmask_b32_e64 v32, v40, v41, s[0:1]
	v_mul_f32_e32 v40, 0x37800000, v32
	v_cndmask_b32_e32 v32, v32, v40, vcc
	v_cmp_class_f32_e32 vcc, v31, v190
	v_fmac_f32_e32 v12, v25, v25
	v_fmac_f32_e32 v12, v28, v28
	v_cndmask_b32_e32 v31, v32, v31, vcc
	v_div_scale_f32 v32, s[0:1], v31, v31, 1.0
	v_rcp_f32_e32 v40, v32
	v_mul_f32_e32 v13, v11, v11
	v_fmac_f32_e32 v13, v7, v7
	v_fmac_f32_e32 v13, v17, v17
	v_fma_f32 v41, -v32, v40, 1.0
	v_fmac_f32_e32 v40, v41, v40
	v_div_scale_f32 v41, vcc, 1.0, v31, 1.0
	v_mul_f32_e32 v83, v41, v40
	v_fma_f32 v85, -v32, v83, v41
	v_fmac_f32_e32 v83, v85, v40
	v_fma_f32 v32, -v32, v83, v41
	v_div_fmas_f32 v32, v32, v40, v83
	v_div_fixup_f32 v40, v32, v31, 1.0
	v_mul_f32_e32 v31, v40, v0
	v_mul_f32_e32 v31, v31, v33
	v_mul_f32_e32 v32, v40, v4
	v_mul_f32_e32 v33, v40, v5
	v_mul_f32_e32 v40, v40, v6
	v_mul_f32_e32 v34, v40, v34
	s_nop 1
	v_mov_b32_dpp v40, v82 quad_perm:[1,0,3,2] row_mask:0xf bank_mask:0xf
	v_mul_f32_e32 v32, v32, v86
	v_fmac_f32_e32 v13, v18, v18
	v_mul_f32_e32 v3, v2, v2
	v_fmac_f32_e32 v3, v8, v8
	s_waitcnt lgkmcnt(0)
	v_add_f32_e32 v40, v82, v40
	s_nop 1
	v_mov_b32_dpp v41, v40 quad_perm:[2,3,0,1] row_mask:0xf bank_mask:0xf
	v_fmac_f32_e32 v3, v10, v10
	v_fmac_f32_e32 v3, v14, v14
	v_mul_f32_e32 v20, v20, v87
	v_mul_f32_e32 v22, v22, v89
	s_waitcnt lgkmcnt(0)
	v_add_f32_e32 v40, v40, v41
	s_nop 1
	v_mov_b32_dpp v41, v40 row_half_mirror row_mask:0xf bank_mask:0xf
	v_mul_f32_e32 v23, v23, v93
	v_mul_f32_e32 v33, v33, v90
	s_waitcnt lgkmcnt(0)
	v_add_f32_e32 v40, v40, v41
	s_nop 1
	v_mov_b32_dpp v41, v40 row_mirror row_mask:0xf bank_mask:0xf
	s_waitcnt lgkmcnt(0)
	v_add_f32_e32 v40, v40, v41
	v_mov_b32_e32 v41, v40
	s_nop 1
	v_permlane16_swap_b32_e32 v40, v41
	s_waitcnt lgkmcnt(0)
	v_add_f32_e32 v40, v40, v41
	v_fmamk_f32 v40, v40, 0x3c000000, v189
	v_cmp_gt_f32_e32 vcc, s2, v40
	v_mul_f32_e32 v41, 0x4f800000, v40
	s_nop 0
	v_cndmask_b32_e32 v40, v40, v41, vcc
	v_sqrt_f32_e32 v41, v40
	s_nop 0
	v_add_u32_e32 v82, -1, v41
	v_fma_f32 v83, -v82, v41, v40
	v_cmp_ge_f32_e64 s[0:1], 0, v83
	v_add_u32_e32 v83, 1, v41
	s_nop 0
	v_cndmask_b32_e64 v82, v41, v82, s[0:1]
	v_fma_f32 v41, -v83, v41, v40
	v_cmp_lt_f32_e64 s[0:1], 0, v41
	s_nop 1
	v_cndmask_b32_e64 v41, v82, v83, s[0:1]
	v_mul_f32_e32 v82, 0x37800000, v41
	v_cndmask_b32_e32 v41, v41, v82, vcc
	v_cmp_class_f32_e32 vcc, v40, v190
	s_nop 1
	v_cndmask_b32_e32 v40, v41, v40, vcc
	v_div_scale_f32 v41, s[0:1], v40, v40, 1.0
	v_rcp_f32_e32 v82, v41
	s_nop 0
	v_fma_f32 v83, -v41, v82, 1.0
	v_fmac_f32_e32 v82, v83, v82
	v_div_scale_f32 v83, vcc, 1.0, v40, 1.0
	v_mul_f32_e32 v85, v83, v82
	v_fma_f32 v86, -v41, v85, v83
	v_fmac_f32_e32 v85, v86, v82
	v_fma_f32 v41, -v41, v85, v83
	v_div_fmas_f32 v41, v41, v82, v85
	v_div_fixup_f32 v82, v41, v40, 1.0
	v_mul_f32_e32 v40, v82, v0
	v_mul_f32_e32 v39, v40, v39
	v_mul_f32_e32 v40, v82, v4
	v_mul_f32_e32 v40, v40, v42
	v_mul_f32_e32 v41, v82, v5
	v_mul_f32_e32 v42, v82, v6
	s_nop 1
	v_mov_b32_dpp v82, v50 quad_perm:[1,0,3,2] row_mask:0xf bank_mask:0xf
	v_mul_f32_e32 v42, v42, v84
	v_mul_f32_e32 v41, v41, v88
	s_waitcnt lgkmcnt(0)
	v_add_f32_e32 v50, v50, v82
	s_nop 1
	v_mov_b32_dpp v82, v50 quad_perm:[2,3,0,1] row_mask:0xf bank_mask:0xf
	s_waitcnt lgkmcnt(0)
	v_add_f32_e32 v50, v50, v82
	s_nop 1
	v_mov_b32_dpp v82, v50 row_half_mirror row_mask:0xf bank_mask:0xf
	s_waitcnt lgkmcnt(0)
	v_add_f32_e32 v50, v50, v82
	s_nop 1
	v_mov_b32_dpp v82, v50 row_mirror row_mask:0xf bank_mask:0xf
	s_waitcnt lgkmcnt(0)
	v_add_f32_e32 v50, v50, v82
	v_mov_b32_e32 v82, v50
	s_nop 1
	v_permlane16_swap_b32_e32 v50, v82
	s_waitcnt lgkmcnt(0)
	v_add_f32_e32 v50, v50, v82
	v_fmamk_f32 v50, v50, 0x3c000000, v189
	v_cmp_gt_f32_e32 vcc, s2, v50
	v_mul_f32_e32 v82, 0x4f800000, v50
	s_nop 0
	v_cndmask_b32_e32 v50, v50, v82, vcc
	v_sqrt_f32_e32 v82, v50
	s_nop 0
	v_add_u32_e32 v83, -1, v82
	v_fma_f32 v84, -v83, v82, v50
	v_cmp_ge_f32_e64 s[0:1], 0, v84
	v_add_u32_e32 v84, 1, v82
	s_nop 0
	v_cndmask_b32_e64 v83, v82, v83, s[0:1]
	v_fma_f32 v82, -v84, v82, v50
	v_cmp_lt_f32_e64 s[0:1], 0, v82
	s_nop 1
	v_cndmask_b32_e64 v82, v83, v84, s[0:1]
	v_mul_f32_e32 v83, 0x37800000, v82
	v_cndmask_b32_e32 v82, v82, v83, vcc
	v_cmp_class_f32_e32 vcc, v50, v190
	s_nop 1
	v_cndmask_b32_e32 v50, v82, v50, vcc
	v_div_scale_f32 v82, s[0:1], v50, v50, 1.0
	v_rcp_f32_e32 v83, v82
	s_nop 0
	v_fma_f32 v84, -v82, v83, 1.0
	v_fmac_f32_e32 v83, v84, v83
	v_div_scale_f32 v84, vcc, 1.0, v50, 1.0
	v_mul_f32_e32 v85, v84, v83
	v_fma_f32 v86, -v82, v85, v84
	v_fmac_f32_e32 v85, v86, v83
	v_fma_f32 v82, -v82, v85, v84
	v_div_fmas_f32 v82, v82, v83, v85
	v_div_fixup_f32 v82, v82, v50, 1.0
	v_mul_f32_e32 v50, v82, v0
	v_mul_f32_e32 v49, v50, v49
	v_mul_f32_e32 v50, v82, v4
	v_mul_f32_e32 v50, v50, v51
	v_mul_f32_e32 v51, v82, v5
	v_mul_f32_e32 v51, v51, v80
	v_mul_f32_e32 v80, v82, v6
	v_mul_f32_e32 v52, v80, v52
	s_nop 1
	v_mov_b32_dpp v80, v60 quad_perm:[1,0,3,2] row_mask:0xf bank_mask:0xf
	s_waitcnt lgkmcnt(0)
; __global__ void __launch_bounds__(NTHR) mega_fwd(Params p) {
;     ...
; #pragma unroll
;                       for (int r = 0; r < 16; ++r) { float q = ss[r]; q += __shfl_xor(q, 1); q += __shfl_xor(q, 2); q += __shfl_xor(q, 4); q += __shfl_xor(q, 8); q += __shfl_xor(q, 16);
;                           const float rstd = 1.0f / sqrtf(q * (1.0f / 128.0f) + EPS);
; #pragma unroll
;                           for (int d = 0; d < 4; ++d) o[d][r] *= rstd * gsub[d]; } }
	v_add_f32_e32 v60, v60, v80
	s_nop 1
	v_mov_b32_dpp v80, v60 quad_perm:[2,3,0,1] row_mask:0xf bank_mask:0xf
	s_waitcnt lgkmcnt(0)
	v_add_f32_e32 v60, v60, v80
	s_nop 1
	v_mov_b32_dpp v80, v60 row_half_mirror row_mask:0xf bank_mask:0xf
	s_waitcnt lgkmcnt(0)
	v_add_f32_e32 v60, v60, v80
	s_nop 1
	v_mov_b32_dpp v80, v60 row_mirror row_mask:0xf bank_mask:0xf
	s_waitcnt lgkmcnt(0)
	v_add_f32_e32 v60, v60, v80
	v_mov_b32_e32 v80, v60
	s_nop 1
	v_permlane16_swap_b32_e32 v60, v80
	s_waitcnt lgkmcnt(0)
	v_add_f32_e32 v60, v60, v80
	v_fmamk_f32 v60, v60, 0x3c000000, v189
	v_cmp_gt_f32_e32 vcc, s2, v60
	v_mul_f32_e32 v80, 0x4f800000, v60
	s_nop 0
	v_cndmask_b32_e32 v60, v60, v80, vcc
	v_sqrt_f32_e32 v80, v60
	s_nop 0
	v_add_u32_e32 v82, -1, v80
	v_fma_f32 v83, -v82, v80, v60
	v_cmp_ge_f32_e64 s[0:1], 0, v83
	v_add_u32_e32 v83, 1, v80
	s_nop 0
	v_cndmask_b32_e64 v82, v80, v82, s[0:1]
	v_fma_f32 v80, -v83, v80, v60
	v_cmp_lt_f32_e64 s[0:1], 0, v80
	s_nop 1
	v_cndmask_b32_e64 v80, v82, v83, s[0:1]
	v_mul_f32_e32 v82, 0x37800000, v80
	v_cndmask_b32_e32 v80, v80, v82, vcc
	v_cmp_class_f32_e32 vcc, v60, v190
	s_nop 1
	v_cndmask_b32_e32 v60, v80, v60, vcc
	v_div_scale_f32 v80, s[0:1], v60, v60, 1.0
	v_rcp_f32_e32 v82, v80
	s_nop 0
	v_fma_f32 v83, -v80, v82, 1.0
	v_fmac_f32_e32 v82, v83, v82
	v_div_scale_f32 v83, vcc, 1.0, v60, 1.0
	v_mul_f32_e32 v84, v83, v82
	v_fma_f32 v85, -v80, v84, v83
	v_fmac_f32_e32 v84, v85, v82
	v_fma_f32 v80, -v80, v84, v83
	v_div_fmas_f32 v80, v80, v82, v84
	v_div_fixup_f32 v80, v80, v60, 1.0
	v_mul_f32_e32 v60, v80, v0
	v_mul_f32_e32 v58, v60, v58
	v_mul_f32_e32 v60, v80, v4
	v_mul_f32_e32 v59, v60, v59
	v_mul_f32_e32 v60, v80, v5
	v_mul_f32_e32 v60, v60, v61
	v_mul_f32_e32 v61, v80, v6
	s_nop 1
	v_mov_b32_dpp v80, v68 quad_perm:[1,0,3,2] row_mask:0xf bank_mask:0xf
	v_mul_f32_e32 v61, v61, v81
	s_waitcnt lgkmcnt(0)
	v_add_f32_e32 v68, v68, v80
	s_nop 1
	v_mov_b32_dpp v80, v68 quad_perm:[2,3,0,1] row_mask:0xf bank_mask:0xf
	s_waitcnt lgkmcnt(0)
	v_add_f32_e32 v68, v68, v80
	s_nop 1
	v_mov_b32_dpp v80, v68 row_half_mirror row_mask:0xf bank_mask:0xf
	s_waitcnt lgkmcnt(0)
	v_add_f32_e32 v68, v68, v80
	s_nop 1
	v_mov_b32_dpp v80, v68 row_mirror row_mask:0xf bank_mask:0xf
	s_waitcnt lgkmcnt(0)
	v_add_f32_e32 v68, v68, v80
	v_mov_b32_e32 v80, v68
	s_nop 1
	v_permlane16_swap_b32_e32 v68, v80
	s_waitcnt lgkmcnt(0)
	v_add_f32_e32 v68, v68, v80
	v_fmamk_f32 v68, v68, 0x3c000000, v189
	v_cmp_gt_f32_e32 vcc, s2, v68
	v_mul_f32_e32 v80, 0x4f800000, v68
	s_nop 0
	v_cndmask_b32_e32 v68, v68, v80, vcc
	v_sqrt_f32_e32 v80, v68
	s_nop 0
	v_add_u32_e32 v81, -1, v80
	v_fma_f32 v82, -v81, v80, v68
	v_cmp_ge_f32_e64 s[0:1], 0, v82
	v_add_u32_e32 v82, 1, v80
	s_nop 0
	v_cndmask_b32_e64 v81, v80, v81, s[0:1]
	v_fma_f32 v80, -v82, v80, v68
	v_cmp_lt_f32_e64 s[0:1], 0, v80
	s_nop 1
	v_cndmask_b32_e64 v80, v81, v82, s[0:1]
	v_mul_f32_e32 v81, 0x37800000, v80
	v_cndmask_b32_e32 v80, v80, v81, vcc
	v_cmp_class_f32_e32 vcc, v68, v190
	s_nop 1
	v_cndmask_b32_e32 v68, v80, v68, vcc
	v_div_scale_f32 v80, s[0:1], v68, v68, 1.0
	v_rcp_f32_e32 v81, v80
	s_nop 0
	v_fma_f32 v82, -v80, v81, 1.0
	v_fmac_f32_e32 v81, v82, v81
	v_div_scale_f32 v82, vcc, 1.0, v68, 1.0
	v_mul_f32_e32 v83, v82, v81
	v_fma_f32 v84, -v80, v83, v82
	v_fmac_f32_e32 v83, v84, v81
	v_fma_f32 v80, -v80, v83, v82
	v_div_fmas_f32 v80, v80, v81, v83
	v_div_fixup_f32 v80, v80, v68, 1.0
	v_mul_f32_e32 v68, v80, v0
	v_mul_f32_e32 v67, v68, v67
	v_mul_f32_e32 v68, v80, v4
	v_mul_f32_e32 v68, v68, v69
	v_mul_f32_e32 v69, v80, v5
	v_mul_f32_e32 v69, v69, v70
	v_mul_f32_e32 v70, v80, v6
	v_mul_f32_e32 v70, v70, v79
	s_nop 1
	v_mov_b32_dpp v79, v74 quad_perm:[1,0,3,2] row_mask:0xf bank_mask:0xf
	s_waitcnt lgkmcnt(0)
	v_add_f32_e32 v74, v74, v79
	s_nop 1
	v_mov_b32_dpp v79, v74 quad_perm:[2,3,0,1] row_mask:0xf bank_mask:0xf
	s_waitcnt lgkmcnt(0)
	v_add_f32_e32 v74, v74, v79
	s_nop 1
	v_mov_b32_dpp v79, v74 row_half_mirror row_mask:0xf bank_mask:0xf
	s_waitcnt lgkmcnt(0)
	v_add_f32_e32 v74, v74, v79
	s_nop 1
	v_mov_b32_dpp v79, v74 row_mirror row_mask:0xf bank_mask:0xf
	s_waitcnt lgkmcnt(0)
	v_add_f32_e32 v74, v74, v79
	v_mov_b32_e32 v79, v74
	s_nop 1
	v_permlane16_swap_b32_e32 v74, v79
	s_waitcnt lgkmcnt(0)
	v_add_f32_e32 v74, v74, v79
	v_fmamk_f32 v74, v74, 0x3c000000, v189
	v_cmp_gt_f32_e32 vcc, s2, v74
	v_mul_f32_e32 v79, 0x4f800000, v74
	s_nop 0
	v_cndmask_b32_e32 v74, v74, v79, vcc
	v_sqrt_f32_e32 v79, v74
	s_nop 0
	v_add_u32_e32 v80, -1, v79
	v_fma_f32 v81, -v80, v79, v74
	v_cmp_ge_f32_e64 s[0:1], 0, v81
	v_add_u32_e32 v81, 1, v79
	s_nop 0
	v_cndmask_b32_e64 v80, v79, v80, s[0:1]
	v_fma_f32 v79, -v81, v79, v74
	v_cmp_lt_f32_e64 s[0:1], 0, v79
	s_nop 1
	v_cndmask_b32_e64 v79, v80, v81, s[0:1]
	v_mul_f32_e32 v80, 0x37800000, v79
	v_cndmask_b32_e32 v79, v79, v80, vcc
	v_cmp_class_f32_e32 vcc, v74, v190
	s_nop 1
	v_cndmask_b32_e32 v74, v79, v74, vcc
	v_div_scale_f32 v79, s[0:1], v74, v74, 1.0
	v_rcp_f32_e32 v80, v79
	s_nop 0
	v_fma_f32 v81, -v79, v80, 1.0
	v_fmac_f32_e32 v80, v81, v80
	v_div_scale_f32 v81, vcc, 1.0, v74, 1.0
	v_mul_f32_e32 v82, v81, v80
	v_fma_f32 v83, -v79, v82, v81
	v_fmac_f32_e32 v82, v83, v80
	v_fma_f32 v79, -v79, v82, v81
	v_div_fmas_f32 v79, v79, v80, v82
	v_div_fixup_f32 v79, v79, v74, 1.0
	v_mul_f32_e32 v74, v79, v0
	v_mul_f32_e32 v64, v74, v64
	v_mul_f32_e32 v74, v79, v4
	v_mul_f32_e32 v72, v74, v72
	v_mul_f32_e32 v74, v79, v5
	v_mul_f32_e32 v74, v74, v76
	v_mul_f32_e32 v76, v79, v6
	v_mul_f32_e32 v76, v76, v78
	s_nop 1
	v_mov_b32_dpp v78, v55 quad_perm:[1,0,3,2] row_mask:0xf bank_mask:0xf
	s_waitcnt lgkmcnt(0)
	v_add_f32_e32 v55, v55, v78
	s_nop 1
	v_mov_b32_dpp v78, v55 quad_perm:[2,3,0,1] row_mask:0xf bank_mask:0xf
	s_waitcnt lgkmcnt(0)
; __global__ void __launch_bounds__(NTHR) mega_fwd(Params p) {
;     ...
; #pragma unroll
;                       for (int r = 0; r < 16; ++r) { float q = ss[r]; q += __shfl_xor(q, 1); q += __shfl_xor(q, 2); q += __shfl_xor(q, 4); q += __shfl_xor(q, 8); q += __shfl_xor(q, 16);
;                           const float rstd = 1.0f / sqrtf(q * (1.0f / 128.0f) + EPS);
; #pragma unroll
;                           for (int d = 0; d < 4; ++d) o[d][r] *= rstd * gsub[d]; } }
	v_add_f32_e32 v55, v55, v78
	s_nop 1
	v_mov_b32_dpp v78, v55 row_half_mirror row_mask:0xf bank_mask:0xf
	s_waitcnt lgkmcnt(0)
	v_add_f32_e32 v55, v55, v78
	s_nop 1
	v_mov_b32_dpp v78, v55 row_mirror row_mask:0xf bank_mask:0xf
	s_waitcnt lgkmcnt(0)
	v_add_f32_e32 v55, v55, v78
	v_mov_b32_e32 v78, v55
	s_nop 1
	v_permlane16_swap_b32_e32 v55, v78
	s_waitcnt lgkmcnt(0)
	v_add_f32_e32 v55, v55, v78
	v_fmamk_f32 v55, v55, 0x3c000000, v189
	v_cmp_gt_f32_e32 vcc, s2, v55
	v_mul_f32_e32 v78, 0x4f800000, v55
	s_nop 0
	v_cndmask_b32_e32 v55, v55, v78, vcc
	v_sqrt_f32_e32 v78, v55
	s_nop 0
	v_add_u32_e32 v79, -1, v78
	v_fma_f32 v80, -v79, v78, v55
	v_cmp_ge_f32_e64 s[0:1], 0, v80
	v_add_u32_e32 v80, 1, v78
	s_nop 0
	v_cndmask_b32_e64 v79, v78, v79, s[0:1]
	v_fma_f32 v78, -v80, v78, v55
	v_cmp_lt_f32_e64 s[0:1], 0, v78
	s_nop 1
	v_cndmask_b32_e64 v78, v79, v80, s[0:1]
	v_mul_f32_e32 v79, 0x37800000, v78
	v_cndmask_b32_e32 v78, v78, v79, vcc
	v_cmp_class_f32_e32 vcc, v55, v190
	s_nop 1
	v_cndmask_b32_e32 v55, v78, v55, vcc
	v_div_scale_f32 v78, s[0:1], v55, v55, 1.0
	v_rcp_f32_e32 v79, v78
	s_nop 0
	v_fma_f32 v80, -v78, v79, 1.0
	v_fmac_f32_e32 v79, v80, v79
	v_div_scale_f32 v80, vcc, 1.0, v55, 1.0
	v_mul_f32_e32 v81, v80, v79
	v_fma_f32 v82, -v78, v81, v80
	v_fmac_f32_e32 v81, v82, v79
	v_fma_f32 v78, -v78, v81, v80
	v_div_fmas_f32 v78, v78, v79, v81
	v_div_fixup_f32 v78, v78, v55, 1.0
	v_mul_f32_e32 v55, v78, v0
	v_mul_f32_e32 v54, v55, v54
	v_mul_f32_e32 v55, v78, v4
	v_mul_f32_e32 v55, v55, v63
	v_mul_f32_e32 v63, v78, v5
	v_mul_f32_e32 v63, v63, v73
	v_mul_f32_e32 v73, v78, v6
	v_mul_f32_e32 v73, v73, v77
	s_nop 1
	v_mov_b32_dpp v77, v65 quad_perm:[1,0,3,2] row_mask:0xf bank_mask:0xf
	s_waitcnt lgkmcnt(0)
	v_add_f32_e32 v65, v65, v77
	s_nop 1
	v_mov_b32_dpp v77, v65 quad_perm:[2,3,0,1] row_mask:0xf bank_mask:0xf
	s_waitcnt lgkmcnt(0)
	v_add_f32_e32 v65, v65, v77
	s_nop 1
	v_mov_b32_dpp v77, v65 row_half_mirror row_mask:0xf bank_mask:0xf
	s_waitcnt lgkmcnt(0)
	v_add_f32_e32 v65, v65, v77
	s_nop 1
	v_mov_b32_dpp v77, v65 row_mirror row_mask:0xf bank_mask:0xf
	s_waitcnt lgkmcnt(0)
	v_add_f32_e32 v65, v65, v77
	v_mov_b32_e32 v77, v65
	s_nop 1
	v_permlane16_swap_b32_e32 v65, v77
	s_waitcnt lgkmcnt(0)
	v_add_f32_e32 v65, v65, v77
	v_fmamk_f32 v65, v65, 0x3c000000, v189
	v_cmp_gt_f32_e32 vcc, s2, v65
	v_mul_f32_e32 v77, 0x4f800000, v65
	s_nop 0
	v_cndmask_b32_e32 v65, v65, v77, vcc
	v_sqrt_f32_e32 v77, v65
	s_nop 0
	v_add_u32_e32 v78, -1, v77
	v_fma_f32 v79, -v78, v77, v65
	v_cmp_ge_f32_e64 s[0:1], 0, v79
	v_add_u32_e32 v79, 1, v77
	s_nop 0
	v_cndmask_b32_e64 v78, v77, v78, s[0:1]
	v_fma_f32 v77, -v79, v77, v65
	v_cmp_lt_f32_e64 s[0:1], 0, v77
	s_nop 1
	v_cndmask_b32_e64 v77, v78, v79, s[0:1]
	v_mul_f32_e32 v78, 0x37800000, v77
	v_cndmask_b32_e32 v77, v77, v78, vcc
	v_cmp_class_f32_e32 vcc, v65, v190
	s_nop 1
	v_cndmask_b32_e32 v65, v77, v65, vcc
	v_div_scale_f32 v77, s[0:1], v65, v65, 1.0
	v_rcp_f32_e32 v78, v77
	s_nop 0
	v_fma_f32 v79, -v77, v78, 1.0
	v_fmac_f32_e32 v78, v79, v78
	v_div_scale_f32 v79, vcc, 1.0, v65, 1.0
	v_mul_f32_e32 v80, v79, v78
	v_fma_f32 v81, -v77, v80, v79
	v_fmac_f32_e32 v80, v81, v78
	v_fma_f32 v77, -v77, v80, v79
	v_div_fmas_f32 v77, v77, v78, v80
	v_div_fixup_f32 v77, v77, v65, 1.0
	v_mul_f32_e32 v65, v77, v0
	v_mul_f32_e32 v47, v65, v47
	v_mul_f32_e32 v65, v77, v4
	v_mul_f32_e32 v57, v65, v57
	v_mul_f32_e32 v65, v77, v5
	v_mul_f32_e32 v65, v65, v71
	v_mul_f32_e32 v71, v77, v6
	v_mul_f32_e32 v71, v71, v75
	s_nop 1
	v_mov_b32_dpp v75, v44 quad_perm:[1,0,3,2] row_mask:0xf bank_mask:0xf
	s_waitcnt lgkmcnt(0)
	v_add_f32_e32 v44, v44, v75
	s_nop 1
	v_mov_b32_dpp v75, v44 quad_perm:[2,3,0,1] row_mask:0xf bank_mask:0xf
	s_waitcnt lgkmcnt(0)
	v_add_f32_e32 v44, v44, v75
	s_nop 1
	v_mov_b32_dpp v75, v44 row_half_mirror row_mask:0xf bank_mask:0xf
	s_waitcnt lgkmcnt(0)
	v_add_f32_e32 v44, v44, v75
	s_nop 1
	v_mov_b32_dpp v75, v44 row_mirror row_mask:0xf bank_mask:0xf
	s_waitcnt lgkmcnt(0)
	v_add_f32_e32 v44, v44, v75
	v_mov_b32_e32 v75, v44
	s_nop 1
	v_permlane16_swap_b32_e32 v44, v75
	s_waitcnt lgkmcnt(0)
	v_add_f32_e32 v44, v44, v75
	v_fmamk_f32 v44, v44, 0x3c000000, v189
	v_cmp_gt_f32_e32 vcc, s2, v44
	v_mul_f32_e32 v75, 0x4f800000, v44
	s_nop 0
	v_cndmask_b32_e32 v44, v44, v75, vcc
	v_sqrt_f32_e32 v75, v44
	s_nop 0
	v_add_u32_e32 v77, -1, v75
	v_fma_f32 v78, -v77, v75, v44
	v_cmp_ge_f32_e64 s[0:1], 0, v78
	v_add_u32_e32 v78, 1, v75
	s_nop 0
	v_cndmask_b32_e64 v77, v75, v77, s[0:1]
	v_fma_f32 v75, -v78, v75, v44
	v_cmp_lt_f32_e64 s[0:1], 0, v75
	s_nop 1
	v_cndmask_b32_e64 v75, v77, v78, s[0:1]
	v_mul_f32_e32 v77, 0x37800000, v75
	v_cndmask_b32_e32 v75, v75, v77, vcc
	v_cmp_class_f32_e32 vcc, v44, v190
	s_nop 1
	v_cndmask_b32_e32 v44, v75, v44, vcc
	v_div_scale_f32 v75, s[0:1], v44, v44, 1.0
	v_rcp_f32_e32 v77, v75
	s_nop 0
	v_fma_f32 v78, -v75, v77, 1.0
	v_fmac_f32_e32 v77, v78, v77
	v_div_scale_f32 v78, vcc, 1.0, v44, 1.0
	v_mul_f32_e32 v79, v78, v77
	v_fma_f32 v80, -v75, v79, v78
	v_fmac_f32_e32 v79, v80, v77
	v_fma_f32 v75, -v75, v79, v78
	v_div_fmas_f32 v75, v75, v77, v79
	v_div_fixup_f32 v75, v75, v44, 1.0
	v_mul_f32_e32 v44, v75, v0
	v_mul_f32_e32 v37, v44, v37
	v_mul_f32_e32 v44, v75, v4
	v_mul_f32_e32 v44, v44, v48
	v_mul_f32_e32 v48, v75, v5
	v_mul_f32_e32 v48, v48, v62
	v_mul_f32_e32 v62, v75, v6
	v_mul_f32_e32 v62, v62, v66
	s_nop 1
	v_mov_b32_dpp v66, v45 quad_perm:[1,0,3,2] row_mask:0xf bank_mask:0xf
	s_waitcnt lgkmcnt(0)
	v_add_f32_e32 v45, v45, v66
	s_nop 1
	v_mov_b32_dpp v66, v45 quad_perm:[2,3,0,1] row_mask:0xf bank_mask:0xf
	s_waitcnt lgkmcnt(0)
	v_add_f32_e32 v45, v45, v66
	s_nop 1
	v_mov_b32_dpp v66, v45 row_half_mirror row_mask:0xf bank_mask:0xf
	s_waitcnt lgkmcnt(0)
; __global__ void __launch_bounds__(NTHR) mega_fwd(Params p) {
;     ...
; #pragma unroll
;                       for (int r = 0; r < 16; ++r) { float q = ss[r]; q += __shfl_xor(q, 1); q += __shfl_xor(q, 2); q += __shfl_xor(q, 4); q += __shfl_xor(q, 8); q += __shfl_xor(q, 16);
;                           const float rstd = 1.0f / sqrtf(q * (1.0f / 128.0f) + EPS);
; #pragma unroll
;                           for (int d = 0; d < 4; ++d) o[d][r] *= rstd * gsub[d]; } }
	v_add_f32_e32 v45, v45, v66
	s_nop 1
	v_mov_b32_dpp v66, v45 row_mirror row_mask:0xf bank_mask:0xf
	s_waitcnt lgkmcnt(0)
	v_add_f32_e32 v45, v45, v66
	v_mov_b32_e32 v66, v45
	s_nop 1
	v_permlane16_swap_b32_e32 v45, v66
	s_waitcnt lgkmcnt(0)
	v_add_f32_e32 v45, v45, v66
	v_fmamk_f32 v45, v45, 0x3c000000, v189
	v_cmp_gt_f32_e32 vcc, s2, v45
	v_mul_f32_e32 v66, 0x4f800000, v45
	s_nop 0
	v_cndmask_b32_e32 v45, v45, v66, vcc
	v_sqrt_f32_e32 v66, v45
	s_nop 0
	v_add_u32_e32 v75, -1, v66
	v_fma_f32 v77, -v75, v66, v45
	v_cmp_ge_f32_e64 s[0:1], 0, v77
	v_add_u32_e32 v77, 1, v66
	s_nop 0
	v_cndmask_b32_e64 v75, v66, v75, s[0:1]
	v_fma_f32 v66, -v77, v66, v45
	v_cmp_lt_f32_e64 s[0:1], 0, v66
	s_nop 1
	v_cndmask_b32_e64 v66, v75, v77, s[0:1]
	v_mul_f32_e32 v75, 0x37800000, v66
	v_cndmask_b32_e32 v66, v66, v75, vcc
	v_cmp_class_f32_e32 vcc, v45, v190
	s_nop 1
	v_cndmask_b32_e32 v45, v66, v45, vcc
	v_div_scale_f32 v66, s[0:1], v45, v45, 1.0
	v_rcp_f32_e32 v75, v66
	s_nop 0
	v_fma_f32 v77, -v66, v75, 1.0
	v_fmac_f32_e32 v75, v77, v75
	v_div_scale_f32 v77, vcc, 1.0, v45, 1.0
	v_mul_f32_e32 v78, v77, v75
	v_fma_f32 v79, -v66, v78, v77
	v_fmac_f32_e32 v78, v79, v75
	v_fma_f32 v66, -v66, v78, v77
	v_div_fmas_f32 v66, v66, v75, v78
	v_div_fixup_f32 v66, v66, v45, 1.0
	v_mul_f32_e32 v45, v66, v0
	v_mul_f32_e32 v29, v45, v29
	v_mul_f32_e32 v45, v66, v4
	v_mul_f32_e32 v38, v45, v38
	v_mul_f32_e32 v45, v66, v5
	v_mul_f32_e32 v45, v45, v53
	v_mul_f32_e32 v53, v66, v6
	v_mul_f32_e32 v53, v53, v56
	s_nop 1
	v_mov_b32_dpp v56, v26 quad_perm:[1,0,3,2] row_mask:0xf bank_mask:0xf
	s_waitcnt lgkmcnt(0)
	v_add_f32_e32 v26, v26, v56
	s_nop 1
	v_mov_b32_dpp v56, v26 quad_perm:[2,3,0,1] row_mask:0xf bank_mask:0xf
	s_waitcnt lgkmcnt(0)
	v_add_f32_e32 v26, v26, v56
	s_nop 1
	v_mov_b32_dpp v56, v26 row_half_mirror row_mask:0xf bank_mask:0xf
	s_waitcnt lgkmcnt(0)
	v_add_f32_e32 v26, v26, v56
	s_nop 1
	v_mov_b32_dpp v56, v26 row_mirror row_mask:0xf bank_mask:0xf
	s_waitcnt lgkmcnt(0)
	v_add_f32_e32 v26, v26, v56
	v_mov_b32_e32 v56, v26
	s_nop 1
	v_permlane16_swap_b32_e32 v26, v56
	s_waitcnt lgkmcnt(0)
	v_add_f32_e32 v26, v26, v56
	v_fmamk_f32 v26, v26, 0x3c000000, v189
	v_cmp_gt_f32_e32 vcc, s2, v26
	v_mul_f32_e32 v56, 0x4f800000, v26
	s_nop 0
	v_cndmask_b32_e32 v26, v26, v56, vcc
	v_sqrt_f32_e32 v56, v26
	s_nop 0
	v_add_u32_e32 v66, -1, v56
	v_fma_f32 v75, -v66, v56, v26
	v_cmp_ge_f32_e64 s[0:1], 0, v75
	v_add_u32_e32 v75, 1, v56
	s_nop 0
	v_cndmask_b32_e64 v66, v56, v66, s[0:1]
	v_fma_f32 v56, -v75, v56, v26
	v_cmp_lt_f32_e64 s[0:1], 0, v56
	s_nop 1
	v_cndmask_b32_e64 v56, v66, v75, s[0:1]
	v_mul_f32_e32 v66, 0x37800000, v56
	v_cndmask_b32_e32 v56, v56, v66, vcc
	v_cmp_class_f32_e32 vcc, v26, v190
	s_nop 1
	v_cndmask_b32_e32 v26, v56, v26, vcc
	v_div_scale_f32 v56, s[0:1], v26, v26, 1.0
	v_rcp_f32_e32 v66, v56
	s_nop 0
	v_fma_f32 v75, -v56, v66, 1.0
	v_fmac_f32_e32 v66, v75, v66
	v_div_scale_f32 v75, vcc, 1.0, v26, 1.0
	v_mul_f32_e32 v77, v75, v66
	v_fma_f32 v78, -v56, v77, v75
	v_fmac_f32_e32 v77, v78, v66
	v_fma_f32 v56, -v56, v77, v75
	v_div_fmas_f32 v56, v56, v66, v77
	v_div_fixup_f32 v56, v56, v26, 1.0
	v_mul_f32_e32 v26, v56, v0
	v_mul_f32_e32 v19, v26, v19
	v_mul_f32_e32 v26, v56, v4
	v_mul_f32_e32 v26, v26, v30
	v_mul_f32_e32 v30, v56, v5
	v_mul_f32_e32 v30, v30, v43
	v_mul_f32_e32 v43, v56, v6
	v_mul_f32_e32 v43, v43, v46
	s_nop 1
	v_mov_b32_dpp v46, v27 quad_perm:[1,0,3,2] row_mask:0xf bank_mask:0xf
	s_waitcnt lgkmcnt(0)
	v_add_f32_e32 v27, v27, v46
	s_nop 1
	v_mov_b32_dpp v46, v27 quad_perm:[2,3,0,1] row_mask:0xf bank_mask:0xf
	s_waitcnt lgkmcnt(0)
	v_add_f32_e32 v27, v27, v46
	s_nop 1
	v_mov_b32_dpp v46, v27 row_half_mirror row_mask:0xf bank_mask:0xf
	s_waitcnt lgkmcnt(0)
	v_add_f32_e32 v27, v27, v46
	s_nop 1
	v_mov_b32_dpp v46, v27 row_mirror row_mask:0xf bank_mask:0xf
	s_waitcnt lgkmcnt(0)
	v_add_f32_e32 v27, v27, v46
	v_mov_b32_e32 v46, v27
	s_nop 1
	v_permlane16_swap_b32_e32 v27, v46
	s_waitcnt lgkmcnt(0)
	v_add_f32_e32 v27, v27, v46
	v_fmamk_f32 v27, v27, 0x3c000000, v189
	v_cmp_gt_f32_e32 vcc, s2, v27
	v_mul_f32_e32 v46, 0x4f800000, v27
	s_nop 0
	v_cndmask_b32_e32 v27, v27, v46, vcc
	v_sqrt_f32_e32 v46, v27
	s_nop 0
	v_add_u32_e32 v56, -1, v46
	v_fma_f32 v66, -v56, v46, v27
	v_cmp_ge_f32_e64 s[0:1], 0, v66
	v_add_u32_e32 v66, 1, v46
	s_nop 0
	v_cndmask_b32_e64 v56, v46, v56, s[0:1]
	v_fma_f32 v46, -v66, v46, v27
	v_cmp_lt_f32_e64 s[0:1], 0, v46
	s_nop 1
	v_cndmask_b32_e64 v46, v56, v66, s[0:1]
	v_mul_f32_e32 v56, 0x37800000, v46
	v_cndmask_b32_e32 v46, v46, v56, vcc
	v_cmp_class_f32_e32 vcc, v27, v190
	s_nop 1
	v_cndmask_b32_e32 v27, v46, v27, vcc
	v_div_scale_f32 v46, s[0:1], v27, v27, 1.0
	v_rcp_f32_e32 v56, v46
	s_nop 0
	v_fma_f32 v66, -v46, v56, 1.0
	v_fmac_f32_e32 v56, v66, v56
	v_div_scale_f32 v66, vcc, 1.0, v27, 1.0
	v_mul_f32_e32 v75, v66, v56
	v_fma_f32 v77, -v46, v75, v66
	v_fmac_f32_e32 v75, v77, v56
	v_fma_f32 v46, -v46, v75, v66
	v_div_fmas_f32 v46, v46, v56, v75
	v_div_fixup_f32 v46, v46, v27, 1.0
	v_mul_f32_e32 v27, v46, v0
	v_mul_f32_e32 v15, v27, v15
	v_mul_f32_e32 v27, v46, v4
	v_mul_f32_e32 v21, v27, v21
	v_mul_f32_e32 v27, v46, v5
	v_mul_f32_e32 v27, v27, v35
	v_mul_f32_e32 v35, v46, v6
	v_mul_f32_e32 v35, v35, v36
	s_nop 1
	v_mov_b32_dpp v36, v12 quad_perm:[1,0,3,2] row_mask:0xf bank_mask:0xf
	s_waitcnt lgkmcnt(0)
	v_add_f32_e32 v12, v12, v36
	s_nop 1
	v_mov_b32_dpp v36, v12 quad_perm:[2,3,0,1] row_mask:0xf bank_mask:0xf
	s_waitcnt lgkmcnt(0)
	v_add_f32_e32 v12, v12, v36
	s_nop 1
	v_mov_b32_dpp v36, v12 row_half_mirror row_mask:0xf bank_mask:0xf
	s_waitcnt lgkmcnt(0)
	v_add_f32_e32 v12, v12, v36
	s_nop 1
	v_mov_b32_dpp v36, v12 row_mirror row_mask:0xf bank_mask:0xf
	s_waitcnt lgkmcnt(0)
; __device__ __forceinline__ int opaque_tid() { int t = threadIdx.x; asm volatile("" : "+v"(t)); return t; }
; __device__ __forceinline__ void store_o_bf16(const att::f32x16 (&o)[4], bf16* base  , unsigned char* lds) {
;     const int tid = opaque_tid(), lane = tid & 63, wave = __builtin_amdgcn_readfirstlane(tid >> 6), r32 = lane & 31, hi = lane >> 5;
;     __syncthreads();
;     float* T = (float*)(lds + wave * 16896);
; __global__ void __launch_bounds__(NTHR) mega_fwd(Params p) {
;     ...
; #pragma unroll
;                       for (int r = 0; r < 16; ++r) { float q = ss[r]; q += __shfl_xor(q, 1); q += __shfl_xor(q, 2); q += __shfl_xor(q, 4); q += __shfl_xor(q, 8); q += __shfl_xor(q, 16);
;                           const float rstd = 1.0f / sqrtf(q * (1.0f / 128.0f) + EPS);
; #pragma unroll
;                           for (int d = 0; d < 4; ++d) o[d][r] *= rstd * gsub[d]; } }
	v_add_f32_e32 v12, v12, v36
	v_mov_b32_e32 v36, v12
	s_nop 1
	v_permlane16_swap_b32_e32 v12, v36
	s_waitcnt lgkmcnt(0)
	v_add_f32_e32 v12, v12, v36
	v_fmamk_f32 v12, v12, 0x3c000000, v189
	v_cmp_gt_f32_e32 vcc, s2, v12
	v_mul_f32_e32 v36, 0x4f800000, v12
	s_nop 0
	v_cndmask_b32_e32 v12, v12, v36, vcc
	v_sqrt_f32_e32 v36, v12
	s_nop 0
	v_add_u32_e32 v46, -1, v36
	v_fma_f32 v56, -v46, v36, v12
	v_cmp_ge_f32_e64 s[0:1], 0, v56
	v_add_u32_e32 v56, 1, v36
	s_nop 0
	v_cndmask_b32_e64 v46, v36, v46, s[0:1]
	v_fma_f32 v36, -v56, v36, v12
	v_cmp_lt_f32_e64 s[0:1], 0, v36
	s_nop 1
	v_cndmask_b32_e64 v36, v46, v56, s[0:1]
	v_mul_f32_e32 v46, 0x37800000, v36
	v_cndmask_b32_e32 v36, v36, v46, vcc
	v_cmp_class_f32_e32 vcc, v12, v190
	s_nop 1
	v_cndmask_b32_e32 v12, v36, v12, vcc
	v_div_scale_f32 v36, s[0:1], v12, v12, 1.0
	v_rcp_f32_e32 v46, v36
	s_nop 0
	v_fma_f32 v56, -v36, v46, 1.0
	v_fmac_f32_e32 v46, v56, v46
	v_div_scale_f32 v56, vcc, 1.0, v12, 1.0
	v_mul_f32_e32 v66, v56, v46
	v_fma_f32 v75, -v36, v66, v56
	v_fmac_f32_e32 v66, v75, v46
	v_fma_f32 v36, -v36, v66, v56
	v_div_fmas_f32 v36, v36, v46, v66
	v_div_fixup_f32 v36, v36, v12, 1.0
	v_mul_f32_e32 v12, v36, v0
	v_mul_f32_e32 v9, v12, v9
	v_mul_f32_e32 v12, v36, v4
	v_mul_f32_e32 v12, v12, v16
	v_mul_f32_e32 v16, v36, v5
	v_mul_f32_e32 v16, v16, v25
	v_mul_f32_e32 v25, v36, v6
	v_mul_f32_e32 v25, v25, v28
	s_nop 1
	v_mov_b32_dpp v28, v13 quad_perm:[1,0,3,2] row_mask:0xf bank_mask:0xf
	s_waitcnt lgkmcnt(0)
	v_add_f32_e32 v13, v13, v28
	s_nop 1
	v_mov_b32_dpp v28, v13 quad_perm:[2,3,0,1] row_mask:0xf bank_mask:0xf
	s_waitcnt lgkmcnt(0)
	v_add_f32_e32 v13, v13, v28
	s_nop 1
	v_mov_b32_dpp v28, v13 row_half_mirror row_mask:0xf bank_mask:0xf
	s_waitcnt lgkmcnt(0)
	v_add_f32_e32 v13, v13, v28
	s_nop 1
	v_mov_b32_dpp v28, v13 row_mirror row_mask:0xf bank_mask:0xf
	s_waitcnt lgkmcnt(0)
	v_add_f32_e32 v13, v13, v28
	v_mov_b32_e32 v28, v13
	s_nop 1
	v_permlane16_swap_b32_e32 v13, v28
	s_waitcnt lgkmcnt(0)
	v_add_f32_e32 v13, v13, v28
	v_fmamk_f32 v13, v13, 0x3c000000, v189
	v_cmp_gt_f32_e32 vcc, s2, v13
	v_mul_f32_e32 v28, 0x4f800000, v13
	s_nop 0
	v_cndmask_b32_e32 v13, v13, v28, vcc
	v_sqrt_f32_e32 v28, v13
	s_nop 0
	v_add_u32_e32 v36, -1, v28
	v_fma_f32 v46, -v36, v28, v13
	v_cmp_ge_f32_e64 s[0:1], 0, v46
	v_add_u32_e32 v46, 1, v28
	s_nop 0
	v_cndmask_b32_e64 v36, v28, v36, s[0:1]
	v_fma_f32 v28, -v46, v28, v13
	v_cmp_lt_f32_e64 s[0:1], 0, v28
	s_nop 1
	v_cndmask_b32_e64 v28, v36, v46, s[0:1]
	v_mul_f32_e32 v36, 0x37800000, v28
	v_cndmask_b32_e32 v28, v28, v36, vcc
	v_cmp_class_f32_e32 vcc, v13, v190
	s_nop 1
	v_cndmask_b32_e32 v13, v28, v13, vcc
	v_div_scale_f32 v28, s[0:1], v13, v13, 1.0
	v_rcp_f32_e32 v36, v28
	s_nop 0
	v_fma_f32 v46, -v28, v36, 1.0
	v_fmac_f32_e32 v36, v46, v36
	v_div_scale_f32 v46, vcc, 1.0, v13, 1.0
	v_mul_f32_e32 v56, v46, v36
	v_fma_f32 v66, -v28, v56, v46
	v_fmac_f32_e32 v56, v66, v36
	v_fma_f32 v28, -v28, v56, v46
	v_div_fmas_f32 v28, v28, v36, v56
	v_div_fixup_f32 v13, v28, v13, 1.0
	v_mul_f32_e32 v28, v13, v0
	v_mul_f32_e32 v7, v28, v7
	v_mul_f32_e32 v28, v13, v4
	v_mul_f32_e32 v11, v28, v11
	v_mul_f32_e32 v28, v13, v5
	v_mul_f32_e32 v13, v13, v6
	v_mul_f32_e32 v13, v13, v18
	s_nop 1
	v_mov_b32_dpp v18, v3 quad_perm:[1,0,3,2] row_mask:0xf bank_mask:0xf
	v_mul_f32_e32 v17, v28, v17
	s_waitcnt lgkmcnt(0)
	v_add_f32_e32 v3, v3, v18
	s_nop 1
	v_mov_b32_dpp v18, v3 quad_perm:[2,3,0,1] row_mask:0xf bank_mask:0xf
	s_waitcnt lgkmcnt(0)
	v_add_f32_e32 v3, v3, v18
	s_nop 1
	v_mov_b32_dpp v18, v3 row_half_mirror row_mask:0xf bank_mask:0xf
	s_waitcnt lgkmcnt(0)
	v_add_f32_e32 v3, v3, v18
	s_nop 1
	v_mov_b32_dpp v18, v3 row_mirror row_mask:0xf bank_mask:0xf
	s_waitcnt lgkmcnt(0)
	v_add_f32_e32 v3, v3, v18
	v_mov_b32_e32 v18, v3
	s_nop 1
	v_permlane16_swap_b32_e32 v3, v18
	s_waitcnt lgkmcnt(0)
	v_add_f32_e32 v3, v3, v18
	v_fmamk_f32 v3, v3, 0x3c000000, v189
	v_cmp_gt_f32_e32 vcc, s2, v3
	v_mul_f32_e32 v18, 0x4f800000, v3
	v_readlane_b32 s2, v253, 7
	v_cndmask_b32_e32 v3, v3, v18, vcc
	v_sqrt_f32_e32 v18, v3
	v_readlane_b32 s3, v253, 8
	v_add_u32_e32 v28, -1, v18
	v_fma_f32 v36, -v28, v18, v3
	v_cmp_ge_f32_e64 s[0:1], 0, v36
	v_add_u32_e32 v36, 1, v18
	s_nop 0
	v_cndmask_b32_e64 v28, v18, v28, s[0:1]
	v_fma_f32 v18, -v36, v18, v3
	v_cmp_lt_f32_e64 s[0:1], 0, v18
	s_nop 1
	v_cndmask_b32_e64 v18, v28, v36, s[0:1]
	v_mul_f32_e32 v28, 0x37800000, v18
	v_cndmask_b32_e32 v18, v18, v28, vcc
	v_cmp_class_f32_e32 vcc, v3, v190
	s_nop 1
	v_cndmask_b32_e32 v3, v18, v3, vcc
	v_div_scale_f32 v18, s[0:1], v3, v3, 1.0
	v_rcp_f32_e32 v28, v18
	s_nop 0
	v_fma_f32 v36, -v18, v28, 1.0
	v_fmac_f32_e32 v28, v36, v28
	v_div_scale_f32 v36, vcc, 1.0, v3, 1.0
	v_mul_f32_e32 v46, v36, v28
	v_fma_f32 v56, -v18, v46, v36
	v_fmac_f32_e32 v46, v56, v28
	v_fma_f32 v18, -v18, v46, v36
	v_div_fmas_f32 v18, v18, v28, v46
	v_div_fixup_f32 v3, v18, v3, 1.0
	v_mul_f32_e32 v0, v3, v0
	v_mul_f32_e32 v0, v0, v2
	v_mul_f32_e32 v2, v3, v4
	v_mul_f32_e32 v4, v3, v5
	v_mov_b32_e32 v5, v188
	v_mul_f32_e32 v2, v2, v8
	v_readfirstlane_b32 s0, v5
	s_ashr_i32 s0, s0, 6
	v_lshrrev_b32_e32 v8, 3, v5
	v_mul_f32_e32 v3, v3, v6
	v_and_b32_e32 v6, 31, v5
	s_mul_i32 s1, s0, 0x4200
	v_and_b32_e32 v8, 4, v8
	s_add_i32 s1, s1, 0
	v_lshlrev_b32_e32 v6, 2, v6
	v_mul_u32_u24_e32 v8, 0x210, v8
	v_add3_u32 v6, s1, v6, v8
	v_add_u32_e32 v8, 0x400, v6
	s_barrier
; __device__ __forceinline__ int opaque_tid() { int t = threadIdx.x; asm volatile("" : "+v"(t)); return t; }
; __device__ __forceinline__ int crow(int r, int hi) { return (r & 3) + 8 * (r >> 2) + 4 * hi; }
; __device__ __forceinline__ unsigned cvtpk(float lo, float hi) { unsigned r; asm volatile("v_cvt_pk_bf16_f32 %0, %1, %2" : "=v"(r) : "v"(lo), "v"(hi)); return r; }
; __device__ __forceinline__ void store_o_bf16(const att::f32x16 (&o)[4], bf16* base  , unsigned char* lds) {
;     const int tid = opaque_tid(), lane = tid & 63, wave = __builtin_amdgcn_readfirstlane(tid >> 6), r32 = lane & 31, hi = lane >> 5;
;     __syncthreads();
;     float* T = (float*)(lds + wave * 16896);
; #pragma unroll
;     for (int r = 0; r < 16; ++r) { float* tp = T + att::crow(r, hi) * 132 + r32;
; #pragma unroll
;         for (int d = 0; d < 4; ++d) tp[32 * d] = o[d][r]; }
; #pragma unroll
;     for (int k = 0; k < 8; ++k) { const int chunk = k * 64 + lane, row = chunk >> 4, c8 = chunk & 15;
;         const f32x4 a = *(const f32x4*)(T + row * 132 + c8 * 8), b = *(const f32x4*)(T + row * 132 + c8 * 8 + 4);
;         v4u w; w.x = att::cvtpk(a.x, a.y); w.y = att::cvtpk(a.z, a.w); w.z = att::cvtpk(b.x, b.y); w.w = att::cvtpk(b.z, b.w);
;         *(v4u*)(base + (size_t)(wave * 32 + row) * DM + c8 * 8) = w; }
; }
	ds_write2_b32 v6, v20, v22 offset1:32
	ds_write2_b32 v6, v23, v24 offset0:64 offset1:96
	ds_write2_b32 v6, v31, v32 offset0:132 offset1:164
	ds_write2_b32 v6, v33, v34 offset0:196 offset1:228
	ds_write2_b32 v8, v39, v40 offset0:8 offset1:40
	ds_write2_b32 v8, v41, v42 offset0:72 offset1:104
	ds_write2_b32 v8, v49, v50 offset0:140 offset1:172
	ds_write2_b32 v8, v51, v52 offset0:204 offset1:236
	v_add_u32_e32 v8, 0x1000, v6
	ds_write2_b32 v8, v58, v59 offset0:32 offset1:64
	ds_write2_b32 v8, v60, v61 offset0:96 offset1:128
	ds_write2_b32 v8, v67, v68 offset0:164 offset1:196
	v_add_u32_e32 v8, 0x1200, v6
	ds_write2_b32 v8, v69, v70 offset0:100 offset1:132
	v_add_u32_e32 v8, 0x1400, v6
	ds_write2_b32 v8, v64, v72 offset0:40 offset1:72
	ds_write2_b32 v8, v74, v76 offset0:104 offset1:136
	ds_write2_b32 v8, v54, v55 offset0:172 offset1:204
	v_add_u32_e32 v8, 0x1600, v6
	ds_write2_b32 v8, v63, v73 offset0:108 offset1:140
	v_add_u32_e32 v8, 0x2000, v6
	ds_write2_b32 v8, v47, v57 offset0:64 offset1:96
	ds_write2_b32 v8, v65, v71 offset0:128 offset1:160
	ds_write2_b32 v8, v37, v44 offset0:196 offset1:228
	v_add_u32_e32 v8, 0x2400, v6
	ds_write2_b32 v8, v48, v62 offset0:4 offset1:36
	ds_write2_b32 v8, v29, v38 offset0:72 offset1:104
	ds_write2_b32 v8, v45, v53 offset0:136 offset1:168
	ds_write2_b32 v8, v19, v26 offset0:204 offset1:236
	v_add_u32_e32 v8, 0x2800, v6
	ds_write2_b32 v8, v30, v43 offset0:12 offset1:44
	v_add_u32_e32 v8, 0x3000, v6
	ds_write2_b32 v8, v15, v21 offset0:96 offset1:128
	ds_write2_b32 v8, v27, v35 offset0:160 offset1:192
	v_add_u32_e32 v8, 0x3200, v6
	ds_write2_b32 v8, v9, v12 offset0:100 offset1:132
	v_add_u32_e32 v8, 0x3400, v6
	ds_write2_b32 v8, v16, v25 offset0:36 offset1:68
	ds_write2_b32 v8, v7, v11 offset0:104 offset1:136
	ds_write2_b32 v8, v17, v13 offset0:168 offset1:200
	v_add_u32_e32 v7, 0x3600, v6
	v_mul_f32_e32 v4, v4, v10
	v_mul_f32_e32 v3, v3, v14
	ds_write2_b32 v7, v0, v2 offset0:108 offset1:140
	v_add_u32_e32 v0, 0x3800, v6
	ds_write2_b32 v0, v4, v3 offset0:44 offset1:76
	v_lshlrev_b32_e32 v0, 3, v5
	v_and_b32_e32 v0, 0x78, v0
	v_lshlrev_b32_e32 v2, 2, v0
	v_lshlrev_b32_e32 v0, 1, v0
	v_lshl_add_u64 v[6:7], s[2:3], 0, v[0:1]
	v_bfe_u32 v0, v5, 4, 2
	v_mul_u32_u24_e32 v3, 0x210, v0
	v_add3_u32 v14, s1, v2, v3
	ds_read_b128 v[2:5], v14
	ds_read_b128 v[8:11], v14 offset:16
	s_waitcnt lgkmcnt(1)
	v_cvt_pk_bf16_f32 v2, v2, v3
	v_cvt_pk_bf16_f32 v3, v4, v5
	s_waitcnt lgkmcnt(0)
	v_cvt_pk_bf16_f32 v4, v8, v9
	v_lshl_or_b32 v8, s0, 5, v0
	v_ashrrev_i32_e32 v9, 31, v8
	v_cvt_pk_bf16_f32 v5, v10, v11
	v_lshlrev_b64 v[10:11], 12, v[8:9]
	v_lshl_add_u64 v[10:11], v[6:7], 0, v[10:11]
	global_store_dwordx4 v[10:11], v[2:5], off
	ds_read_b128 v[2:5], v14 offset:2112
	ds_read_b128 v[10:13], v14 offset:2128
	s_waitcnt lgkmcnt(1)
	v_cvt_pk_bf16_f32 v2, v2, v3
	v_cvt_pk_bf16_f32 v3, v4, v5
	s_waitcnt lgkmcnt(0)
	v_cvt_pk_bf16_f32 v4, v10, v11
	v_or_b32_e32 v10, 4, v8
	v_ashrrev_i32_e32 v11, 31, v10
	v_lshlrev_b64 v[10:11], 12, v[10:11]
	v_lshl_add_u64 v[10:11], v[6:7], 0, v[10:11]
	v_cvt_pk_bf16_f32 v5, v12, v13
	global_store_dwordx4 v[10:11], v[2:5], off
	ds_read_b128 v[2:5], v14 offset:4224
	ds_read_b128 v[10:13], v14 offset:4240
	s_waitcnt lgkmcnt(1)
	v_cvt_pk_bf16_f32 v2, v2, v3
	v_cvt_pk_bf16_f32 v3, v4, v5
	s_waitcnt lgkmcnt(0)
	v_cvt_pk_bf16_f32 v4, v10, v11
	v_or_b32_e32 v10, 8, v8
	v_ashrrev_i32_e32 v11, 31, v10
	v_lshlrev_b64 v[10:11], 12, v[10:11]
	v_lshl_add_u64 v[10:11], v[6:7], 0, v[10:11]
	v_cvt_pk_bf16_f32 v5, v12, v13
	global_store_dwordx4 v[10:11], v[2:5], off
	ds_read_b128 v[2:5], v14 offset:6336
	ds_read_b128 v[10:13], v14 offset:6352
	s_waitcnt lgkmcnt(1)
	v_cvt_pk_bf16_f32 v2, v2, v3
	v_cvt_pk_bf16_f32 v3, v4, v5
	s_waitcnt lgkmcnt(0)
	v_cvt_pk_bf16_f32 v4, v10, v11
	v_or_b32_e32 v10, 12, v8
	v_ashrrev_i32_e32 v11, 31, v10
	v_lshlrev_b64 v[10:11], 12, v[10:11]
	v_lshl_add_u64 v[10:11], v[6:7], 0, v[10:11]
	v_cvt_pk_bf16_f32 v5, v12, v13
	global_store_dwordx4 v[10:11], v[2:5], off
	ds_read_b128 v[2:5], v14 offset:8448
	ds_read_b128 v[10:13], v14 offset:8464
	s_waitcnt lgkmcnt(1)
	v_cvt_pk_bf16_f32 v2, v2, v3
	v_cvt_pk_bf16_f32 v3, v4, v5
	s_waitcnt lgkmcnt(0)
	v_cvt_pk_bf16_f32 v4, v10, v11
	v_or_b32_e32 v10, 16, v8
	v_ashrrev_i32_e32 v11, 31, v10
	v_lshlrev_b64 v[10:11], 12, v[10:11]
	v_lshl_add_u64 v[10:11], v[6:7], 0, v[10:11]
	v_cvt_pk_bf16_f32 v5, v12, v13
	global_store_dwordx4 v[10:11], v[2:5], off
	ds_read_b128 v[2:5], v14 offset:10560
	ds_read_b128 v[10:13], v14 offset:10576
	s_waitcnt lgkmcnt(1)
	v_cvt_pk_bf16_f32 v2, v2, v3
	v_cvt_pk_bf16_f32 v3, v4, v5
	s_waitcnt lgkmcnt(0)
	v_cvt_pk_bf16_f32 v4, v10, v11
	v_or_b32_e32 v10, 20, v8
	v_ashrrev_i32_e32 v11, 31, v10
	v_lshlrev_b64 v[10:11], 12, v[10:11]
	v_lshl_add_u64 v[10:11], v[6:7], 0, v[10:11]
	v_cvt_pk_bf16_f32 v5, v12, v13
	global_store_dwordx4 v[10:11], v[2:5], off
	ds_read_b128 v[2:5], v14 offset:12672
	ds_read_b128 v[10:13], v14 offset:12688
	s_waitcnt lgkmcnt(1)
	v_cvt_pk_bf16_f32 v2, v2, v3
	v_cvt_pk_bf16_f32 v3, v4, v5
	s_waitcnt lgkmcnt(0)
	v_cvt_pk_bf16_f32 v4, v10, v11
	v_or_b32_e32 v10, 24, v8
	v_ashrrev_i32_e32 v11, 31, v10
	v_lshlrev_b64 v[10:11], 12, v[10:11]
	v_lshl_add_u64 v[10:11], v[6:7], 0, v[10:11]
	v_cvt_pk_bf16_f32 v5, v12, v13
	global_store_dwordx4 v[10:11], v[2:5], off
	ds_read_b128 v[2:5], v14 offset:14784
	ds_read_b128 v[10:13], v14 offset:14800
	v_or_b32_e32 v8, 28, v8
	s_waitcnt lgkmcnt(1)
	v_cvt_pk_bf16_f32 v2, v2, v3
	v_cvt_pk_bf16_f32 v3, v4, v5
	s_waitcnt lgkmcnt(0)
	v_cvt_pk_bf16_f32 v4, v10, v11
	v_cvt_pk_bf16_f32 v5, v12, v13

; #define SBAR() __builtin_amdgcn_sched_barrier(0)
; __device__ __forceinline__ void finishSM(f32x16& p0, f32x16& p1, float alpha, float& l_reg, bf16x8& pa0, bf16x8& pa1, bf16x8& pa2, bf16x8& pa3) {
; #pragma unroll
;   for (int r = 0; r < 16; ++r) p1[r] = __builtin_amdgcn_exp2f(p1[r]);
;   float ps = 0;
; #pragma unroll
;   for (int r = 0; r < 16; ++r) ps += p0[r];
; #pragma unroll
;   for (int r = 0; r < 16; ++r) ps += p1[r];
;   { auto rr = __builtin_amdgcn_permlane32_swap(__float_as_uint(ps), __float_as_uint(ps), false, false);
;     ps = __uint_as_float(rr[0]) + __uint_as_float(rr[1]); }
;   l_reg = l_reg * alpha + ps;
;     ...
;   PK4(p0, 0, pa0); PK4(p0, 8, pa1); PK4(p1, 0, pa2); PK4(p1, 8, pa3);
;     ...
; }
; template <int DK, bool QL>
; __device__ __forceinline__ void qkt(f32x16& p0, f32x16& p1, const bf16* Ks, const bf16x8* qr, const char* ql, int r32, int hi) {
;   p0 = f32x16{}; p1 = f32x16{};
; #pragma unroll
;   for (int d0 = 0; d0 < DK / 16; ++d0) { int cb = (d0 * 16 + hi * 8) * 2;
;     const bf16x8 qv = QL ? *reinterpret_cast<const bf16x8*>(ql + d0 * 1024) : qr[d0];
;     bf16x8 b0 = *reinterpret_cast<const bf16x8*>((const char*)Ks + kswz<DK>(r32, cb));
;     bf16x8 b1 = *reinterpret_cast<const bf16x8*>((const char*)Ks + kswz<DK>(32 + r32, cb));
;     p0 = __builtin_amdgcn_mfma_f32_32x32x16_bf16(b0, qv, p0, 0, 0, 0);
;     p1 = __builtin_amdgcn_mfma_f32_32x32x16_bf16(b1, qv, p1, 0, 0, 0); }
; }
; template <int OFF> __device__ __forceinline__ s16x4 tr_read(int vb) {
;   s16x4 r; asm volatile("ds_read_b64_tr_b16 %0, %1 offset:%2" : "=&v"(r) : "v"(vb), "i"(OFF) : "memory"); return r;
; }
; template <int D0> __device__ __forceinline__ void pv_one(f32x16& od, int vb, bf16x8 pa0, bf16x8 pa1, bf16x8 pa2, bf16x8 pa3) {
;   const s16x4 l0 = tr_read<v_rd_off(D0, 0, 0)>(vb), h0 = tr_read<v_rd_off(D0, 0, 1)>(vb), l1 = tr_read<v_rd_off(D0, 1, 0)>(vb), h1 = tr_read<v_rd_off(D0, 1, 1)>(vb);
;   const s16x4 l2 = tr_read<v_rd_off(D0, 2, 0)>(vb), h2 = tr_read<v_rd_off(D0, 2, 1)>(vb), l3 = tr_read<v_rd_off(D0, 3, 0)>(vb), h3 = tr_read<v_rd_off(D0, 3, 1)>(vb);
;   asm volatile("s_waitcnt lgkmcnt(0)" ::: "memory"); SBAR();
;     ...
;   od = __builtin_amdgcn_mfma_f32_32x32x16_bf16(pa0, PK(l0, h0), od, 0, 0, 0);
;   od = __builtin_amdgcn_mfma_f32_32x32x16_bf16(pa1, PK(l1, h1), od, 0, 0, 0);
;   od = __builtin_amdgcn_mfma_f32_32x32x16_bf16(pa2, PK(l2, h2), od, 0, 0, 0);
.LBB0_682:
	ds_read_b128 v[66:69], v212 offset:49152
	ds_read_b128 v[70:73], v212 offset:53248
	ds_read_b128 v[182:185], v217 offset:49152
	ds_read_b128 v[190:193], v217 offset:53248
	ds_read_b128 v[168:171], v218 offset:49152
	ds_read_b128 v[194:197], v218 offset:53248
	v_exp_f32_e32 v143, v138
	v_add_f32_e32 v138, 0, v177
	v_add_f32_e32 v138, v226, v138
	s_waitcnt lgkmcnt(5)
	v_mfma_f32_32x32x16_bf16 v[82:97], v[66:69], v[110:113], 0
	v_add_f32_e32 v138, v161, v138
	v_add_f32_e32 v138, v223, v138
	v_add_f32_e32 v138, v153, v138
	ds_read_b128 v[228:231], v216 offset:49152
	ds_read_b128 v[232:235], v216 offset:53248
	v_add_f32_e32 v138, v176, v138
	v_add_f32_e32 v138, v152, v138
	v_add_f32_e32 v138, v160, v138
	s_waitcnt lgkmcnt(6)
	v_mfma_f32_32x32x16_bf16 v[66:81], v[70:73], v[110:113], 0
	v_add_f32_e32 v138, v149, v138
	v_add_f32_e32 v138, v151, v138
	v_add_f32_e32 v138, v147, v138
	v_add_f32_e32 v138, v150, v138
	v_add_f32_e32 v138, v145, v138
	v_exp_f32_e32 v164, v139
	v_add_f32_e32 v138, v148, v138
	s_waitcnt lgkmcnt(1)
	v_mfma_f32_32x32x16_bf16 v[82:97], v[228:231], v[106:109], v[82:97]
	v_exp_f32_e32 v136, v136
	v_add_f32_e32 v138, v144, v138
	v_exp_f32_e32 v137, v137
	v_add_f32_e32 v138, v146, v138
	v_exp_f32_e32 v130, v130
	v_add_f32_e32 v138, v143, v138
	v_exp_f32_e32 v131, v131
	s_waitcnt lgkmcnt(0)
	v_mfma_f32_32x32x16_bf16 v[66:81], v[232:235], v[106:109], v[66:81]
	v_add_f32_e32 v138, v164, v138
	v_exp_f32_e32 v128, v128
	v_add_f32_e32 v138, v136, v138
	v_exp_f32_e32 v129, v129
	v_add_f32_e32 v138, v137, v138
	v_exp_f32_e32 v126, v126
	s_waitcnt lgkmcnt(0)
	v_mfma_f32_32x32x16_bf16 v[82:97], v[182:185], v[98:101], v[82:97]
	v_add_f32_e32 v138, v130, v138
	v_exp_f32_e32 v127, v127
	v_add_f32_e32 v138, v131, v138
	v_exp_f32_e32 v165, v140
	v_add_f32_e32 v138, v128, v138
	v_exp_f32_e32 v166, v141
	v_add_f32_e32 v138, v129, v138
	s_waitcnt lgkmcnt(0)
	v_mfma_f32_32x32x16_bf16 v[66:81], v[190:193], v[98:101], v[66:81]
	v_exp_f32_e32 v134, v134
	v_add_f32_e32 v138, v126, v138
	v_exp_f32_e32 v135, v135
	v_add_f32_e32 v138, v127, v138
	v_exp_f32_e32 v132, v132
	v_add_f32_e32 v138, v165, v138
	s_waitcnt lgkmcnt(0)
	v_mfma_f32_32x32x16_bf16 v[82:97], v[168:171], v[102:105], v[82:97]
	v_exp_f32_e32 v133, v133
	v_add_f32_e32 v138, v166, v138
	v_add_f32_e32 v138, v134, v138
	v_add_f32_e32 v138, v135, v138
	v_add_f32_e32 v138, v132, v138
	v_add_f32_e32 v220, v133, v138
	v_mov_b32_e32 v221, v220
	s_waitcnt lgkmcnt(0)
	v_mfma_f32_32x32x16_bf16 v[66:81], v[194:197], v[102:105], v[66:81]
	v_cvt_pk_bf16_f32 v138, v177, v226
	v_cvt_pk_bf16_f32 v139, v161, v223
	v_cvt_pk_bf16_f32 v140, v153, v176
	v_cvt_pk_bf16_f32 v141, v152, v160
	v_cvt_pk_bf16_f32 v222, v149, v151
	v_cvt_pk_bf16_f32 v223, v147, v150
	v_cvt_pk_bf16_f32 v224, v145, v148
	v_permlane32_swap_b32_e32 v220, v221
	v_permlane32_swap_b32_e32 v138, v140
	v_cvt_pk_bf16_f32 v225, v144, v146
	v_permlane32_swap_b32_e32 v222, v224
	v_cvt_pk_bf16_f32 v144, v143, v164
	v_cvt_pk_bf16_f32 v145, v136, v137
	v_cvt_pk_bf16_f32 v146, v130, v131
	v_cvt_pk_bf16_f32 v147, v128, v129
	v_cvt_pk_bf16_f32 v148, v126, v127
	v_cvt_pk_bf16_f32 v149, v165, v166
	v_cvt_pk_bf16_f32 v150, v134, v135
	v_cvt_pk_bf16_f32 v151, v132, v133
	v_permlane32_swap_b32_e32 v139, v141
	v_permlane32_swap_b32_e32 v223, v225
	v_permlane32_swap_b32_e32 v144, v146
	v_permlane32_swap_b32_e32 v145, v147
	v_permlane32_swap_b32_e32 v148, v150
	v_permlane32_swap_b32_e32 v149, v151
	v_readlane_b32 s2, v254, 32
	v_readlane_b32 s3, v254, 33
	s_mov_b32 s4, 0xe0e0000
	s_mov_b32 s5, 0xe130000
	v_lshl_add_u64 v[160:161], v[156:157], 0, s[2:3]
	v_add_co_u32_e32 v126, vcc, s4, v160
	v_lshl_add_u64 v[176:177], v[158:159], 0, s[2:3]
	s_nop 0
	v_addc_co_u32_e32 v127, vcc, 0, v161, vcc
	v_add_co_u32_e32 v130, vcc, s5, v160
	s_nop 1
	v_addc_co_u32_e32 v131, vcc, 0, v161, vcc
	v_add_co_u32_e32 v134, vcc, s4, v176
	global_load_dwordx4 v[126:129], v[126:127], off offset:2048
	s_nop 0
	global_load_dwordx4 v[130:133], v[130:131], off offset:2048
	v_addc_co_u32_e32 v135, vcc, 0, v177, vcc
	global_load_dwordx4 v[134:137], v[134:135], off offset:1024
	ds_read_b64_tr_b16 v[226:227], v211 offset:0
	ds_read_b64_tr_b16 v[228:229], v211 offset:0x800
	ds_read_b64_tr_b16 v[230:231], v211 offset:0x1000
	ds_read_b64_tr_b16 v[232:233], v211 offset:0x1800
	ds_read_b64_tr_b16 v[234:235], v211 offset:0x2000
	ds_read_b64_tr_b16 v[236:237], v211 offset:0x2800
	ds_read_b64_tr_b16 v[238:239], v211 offset:0x3000
	ds_read_b64_tr_b16 v[240:241], v211 offset:0x3800
	s_waitcnt lgkmcnt(6)
	s_nop 0
	v_mfma_f32_32x32x16_bf16 v[18:33], v[138:141], v[226:229], v[18:33]
	ds_read_b64_tr_b16 v[226:227], v211 offset:0x200
	ds_read_b64_tr_b16 v[228:229], v211 offset:0xa00
	s_waitcnt lgkmcnt(6)
	v_mfma_f32_32x32x16_bf16 v[18:33], v[222:225], v[230:233], v[18:33]
	ds_read_b64_tr_b16 v[230:231], v211 offset:0x1200
	ds_read_b64_tr_b16 v[232:233], v211 offset:0x1a00
	s_waitcnt lgkmcnt(6)
	v_mfma_f32_32x32x16_bf16 v[18:33], v[144:147], v[234:237], v[18:33]
	ds_read_b64_tr_b16 v[234:235], v211 offset:0x2200
	ds_read_b64_tr_b16 v[236:237], v211 offset:0x2a00
	s_waitcnt lgkmcnt(6)
	v_mfma_f32_32x32x16_bf16 v[18:33], v[148:151], v[238:241], v[18:33]
	ds_read_b64_tr_b16 v[238:239], v211 offset:0x3200
	ds_read_b64_tr_b16 v[240:241], v211 offset:0x3a00
	s_waitcnt lgkmcnt(6)
	v_mfma_f32_32x32x16_bf16 v[2:17], v[138:141], v[226:229], v[2:17]
	ds_read_b64_tr_b16 v[226:227], v211 offset:0x400
	ds_read_b64_tr_b16 v[228:229], v211 offset:0xc00
	s_waitcnt lgkmcnt(6)
	v_mfma_f32_32x32x16_bf16 v[2:17], v[222:225], v[230:233], v[2:17]
	ds_read_b64_tr_b16 v[230:231], v211 offset:0x1400
	ds_read_b64_tr_b16 v[232:233], v211 offset:0x1c00
	s_waitcnt lgkmcnt(6)
; #define SBAR() __builtin_amdgcn_sched_barrier(0)
; __device__ __forceinline__ void partialSM(f32x16& p0, f32x16& p1, float& m_reg, float& mn, float& alpha, float C, float thrRaw) {
;   float pmax = p0[0];
; #pragma unroll
;   for (int r = 1; r < 16; ++r) pmax = fmaxf(pmax, p0[r]);
; #pragma unroll
;   for (int r = 0; r < 16; ++r) pmax = fmaxf(pmax, p1[r]);
;   { auto rr = __builtin_amdgcn_permlane32_swap(__float_as_uint(pmax), __float_as_uint(pmax), false, false);
;     pmax = fmaxf(__uint_as_float(rr[0]), __uint_as_float(rr[1])); }
;   if (__builtin_expect(__all(pmax - m_reg <= thrRaw), 1)) { mn = m_reg; alpha = 1.f; }
;   else { mn = fmaxf(m_reg, pmax); alpha = __builtin_amdgcn_exp2f((m_reg - mn) * C); m_reg = mn; }
;   float mnC = -mn * C;
; #pragma unroll
;   for (int r = 0; r < 16; ++r) p0[r] = fmaf(p0[r], C, mnC);
; #pragma unroll
;   for (int r = 0; r < 16; ++r) p1[r] = fmaf(p1[r], C, mnC);
; #pragma unroll
;   for (int r = 0; r < 16; ++r) p0[r] = __builtin_amdgcn_exp2f(p0[r]);
; }
; template <int OFF> __device__ __forceinline__ s16x4 tr_read(int vb) {
;   s16x4 r; asm volatile("ds_read_b64_tr_b16 %0, %1 offset:%2" : "=&v"(r) : "v"(vb), "i"(OFF) : "memory"); return r;
; }
; template <int D0> __device__ __forceinline__ void pv_one(f32x16& od, int vb, bf16x8 pa0, bf16x8 pa1, bf16x8 pa2, bf16x8 pa3) {
;   const s16x4 l0 = tr_read<v_rd_off(D0, 0, 0)>(vb), h0 = tr_read<v_rd_off(D0, 0, 1)>(vb), l1 = tr_read<v_rd_off(D0, 1, 0)>(vb), h1 = tr_read<v_rd_off(D0, 1, 1)>(vb);
;   const s16x4 l2 = tr_read<v_rd_off(D0, 2, 0)>(vb), h2 = tr_read<v_rd_off(D0, 2, 1)>(vb), l3 = tr_read<v_rd_off(D0, 3, 0)>(vb), h3 = tr_read<v_rd_off(D0, 3, 1)>(vb);
;   asm volatile("s_waitcnt lgkmcnt(0)" ::: "memory"); SBAR();
;     ...
;   od = __builtin_amdgcn_mfma_f32_32x32x16_bf16(pa0, PK(l0, h0), od, 0, 0, 0);
;   od = __builtin_amdgcn_mfma_f32_32x32x16_bf16(pa1, PK(l1, h1), od, 0, 0, 0);
;   od = __builtin_amdgcn_mfma_f32_32x32x16_bf16(pa2, PK(l2, h2), od, 0, 0, 0);
;   od = __builtin_amdgcn_mfma_f32_32x32x16_bf16(pa3, PK(l3, h3), od, 0, 0, 0);
;     ...
; }
; __device__ __forceinline__ void pv_d0(f32x16* o, int vb, bf16x8 pa0, bf16x8 pa1, bf16x8 pa2, bf16x8 pa3) {
;   pv_one<0>(o[0], vb, pa0, pa1, pa2, pa3); pv_one<1>(o[1], vb, pa0, pa1, pa2, pa3); pv_one<2>(o[2], vb, pa0, pa1, pa2, pa3); pv_one<3>(o[3], vb, pa0, pa1, pa2, pa3);
	v_mfma_f32_32x32x16_bf16 v[2:17], v[144:147], v[234:237], v[2:17]
	ds_read_b64_tr_b16 v[234:235], v211 offset:0x2400
	ds_read_b64_tr_b16 v[236:237], v211 offset:0x2c00
	s_waitcnt lgkmcnt(6)
	v_mfma_f32_32x32x16_bf16 v[2:17], v[148:151], v[238:241], v[2:17]
	ds_read_b64_tr_b16 v[238:239], v211 offset:0x3400
	ds_read_b64_tr_b16 v[240:241], v211 offset:0x3c00
	s_waitcnt lgkmcnt(6)
	v_mfma_f32_32x32x16_bf16 v[50:65], v[138:141], v[226:229], v[50:65]
	ds_read_b64_tr_b16 v[226:227], v211 offset:0x600
	ds_read_b64_tr_b16 v[228:229], v211 offset:0xe00
	s_waitcnt lgkmcnt(6)
	v_mfma_f32_32x32x16_bf16 v[50:65], v[222:225], v[230:233], v[50:65]
	ds_read_b64_tr_b16 v[230:231], v211 offset:0x1600
	ds_read_b64_tr_b16 v[232:233], v211 offset:0x1e00
	s_waitcnt lgkmcnt(6)
	v_mfma_f32_32x32x16_bf16 v[50:65], v[144:147], v[234:237], v[50:65]
	ds_read_b64_tr_b16 v[234:235], v211 offset:0x2600
	ds_read_b64_tr_b16 v[236:237], v211 offset:0x2e00
	s_waitcnt lgkmcnt(6)
	v_mfma_f32_32x32x16_bf16 v[50:65], v[148:151], v[238:241], v[50:65]
	ds_read_b64_tr_b16 v[238:239], v211 offset:0x3600
	ds_read_b64_tr_b16 v[240:241], v211 offset:0x3e00
	s_waitcnt lgkmcnt(6)
	v_mfma_f32_32x32x16_bf16 v[34:49], v[138:141], v[226:229], v[34:49]
	v_max_f32_e32 v138, v83, v83
	v_max_f32_e32 v139, v82, v82
	v_max_f32_e32 v138, v139, v138
	v_max3_f32 v138, v138, v84, v85
	v_max3_f32 v138, v138, v86, v87
	v_max3_f32 v138, v138, v88, v89
	v_max3_f32 v138, v138, v90, v91
	v_max3_f32 v138, v138, v92, v93
	v_max3_f32 v138, v138, v94, v95
	s_waitcnt lgkmcnt(4)
	v_mfma_f32_32x32x16_bf16 v[34:49], v[222:225], v[230:233], v[34:49]
	v_max3_f32 v138, v138, v96, v97
	v_max3_f32 v138, v138, v66, v67
	v_max3_f32 v138, v138, v68, v69
	v_max3_f32 v138, v138, v70, v71
	v_max3_f32 v138, v138, v72, v73
	v_max3_f32 v138, v138, v74, v75
	v_max3_f32 v138, v138, v76, v77
	v_max3_f32 v138, v138, v78, v79
	s_waitcnt lgkmcnt(2)
	v_mfma_f32_32x32x16_bf16 v[34:49], v[144:147], v[234:237], v[34:49]
	v_max3_f32 v138, v138, v80, v81
	v_mov_b32_e32 v139, v138
	s_nop 1
	v_permlane32_swap_b32_e32 v138, v139
	v_max_f32_e32 v139, v139, v139
	v_max_f32_e32 v138, v138, v138
	v_max_f32_e32 v138, v138, v139
	v_sub_f32_e32 v139, v138, v142
	s_mov_b32 s2, 0x42800000
	v_cmp_ge_f32_e32 vcc, s2, v139
	v_max_f32_e32 v139, v142, v142
	v_max_f32_e32 v138, v139, v138
	s_waitcnt lgkmcnt(0)
	v_mfma_f32_32x32x16_bf16 v[34:49], v[148:151], v[238:241], v[34:49]
	v_sub_f32_e32 v139, v142, v138
	v_mul_f32_e32 v139, 0x3e38aa3b, v139
	v_exp_f32_e32 v139, v139
	s_cmp_eq_u64 vcc, exec
	s_cselect_b64 s[2:3], -1, 0
	s_waitcnt vmcnt(3)
	v_cndmask_b32_e64 v222, v139, 1.0, s[2:3]
	v_cmp_gt_f32_e32 vcc, 1.0, v222
	s_waitcnt vmcnt(3)
	ds_write_b128 v213, v[122:125] offset:32768
	s_cbranch_vccz .LBB0_686
	s_and_saveexec_b64 s[4:5], s[0:1]
	ds_write_b32 v208, v222 offset:128
	s_or_b64 exec, exec, s[4:5]
	s_waitcnt lgkmcnt(0)
	v_add_u32_e32 v139, v207, v0
	ds_read_b128 v[144:147], v139 offset:128
	ds_read_b128 v[148:151], v139 offset:160
	ds_read_b128 v[224:227], v139 offset:192
	ds_read_b128 v[228:231], v139 offset:224
	s_waitcnt lgkmcnt(3)
	v_pk_mul_f32 v[2:3], v[144:145], v[2:3]
	v_pk_mul_f32 v[4:5], v[4:5], v[146:147]
	s_waitcnt lgkmcnt(2)
	v_pk_mul_f32 v[6:7], v[6:7], v[148:149]
	v_pk_mul_f32 v[8:9], v[8:9], v[150:151]
	s_waitcnt lgkmcnt(1)
	v_pk_mul_f32 v[10:11], v[10:11], v[224:225]
	v_pk_mul_f32 v[12:13], v[12:13], v[226:227]
	s_waitcnt lgkmcnt(0)
	v_pk_mul_f32 v[14:15], v[14:15], v[228:229]
	v_pk_mul_f32 v[30:31], v[30:31], v[228:229]
	v_pk_mul_f32 v[26:27], v[26:27], v[224:225]
	v_pk_mul_f32 v[22:23], v[22:23], v[148:149]
	v_pk_mul_f32 v[32:33], v[32:33], v[230:231]
	v_pk_mul_f32 v[28:29], v[28:29], v[226:227]
	v_pk_mul_f32 v[24:25], v[24:25], v[150:151]
	v_pk_mul_f32 v[20:21], v[20:21], v[146:147]
	v_pk_mul_f32 v[18:19], v[18:19], v[144:145]
	v_pk_mul_f32 v[16:17], v[16:17], v[230:231]
	v_pk_mul_f32 v[34:35], v[144:145], v[34:35]
	v_pk_mul_f32 v[36:37], v[36:37], v[146:147]
	v_pk_mul_f32 v[38:39], v[38:39], v[148:149]
	v_pk_mul_f32 v[40:41], v[40:41], v[150:151]
	v_pk_mul_f32 v[42:43], v[42:43], v[224:225]
	v_pk_mul_f32 v[44:45], v[44:45], v[226:227]
	v_pk_mul_f32 v[46:47], v[46:47], v[228:229]
	v_pk_mul_f32 v[62:63], v[62:63], v[228:229]
	v_pk_mul_f32 v[58:59], v[58:59], v[224:225]
	v_pk_mul_f32 v[54:55], v[54:55], v[148:149]
	v_pk_mul_f32 v[64:65], v[64:65], v[230:231]
	v_pk_mul_f32 v[60:61], v[60:61], v[226:227]
	v_pk_mul_f32 v[56:57], v[56:57], v[150:151]
	v_pk_mul_f32 v[52:53], v[52:53], v[146:147]
	v_pk_mul_f32 v[50:51], v[50:51], v[144:145]
	v_pk_mul_f32 v[48:49], v[48:49], v[230:231]
; __device__ __forceinline__ void partialSM(f32x16& p0, f32x16& p1, float& m_reg, float& mn, float& alpha, float C, float thrRaw) {
;     ...
;   float mnC = -mn * C;
; #pragma unroll
;   for (int r = 0; r < 16; ++r) p0[r] = fmaf(p0[r], C, mnC);
; #pragma unroll
;   for (int r = 0; r < 16; ++r) p1[r] = fmaf(p1[r], C, mnC);
; #pragma unroll
;   for (int r = 0; r < 16; ++r) p0[r] = __builtin_amdgcn_exp2f(p0[r]);
; }
; __device__ __forceinline__ void finishSM(f32x16& p0, f32x16& p1, float alpha, float& l_reg, bf16x8& pa0, bf16x8& pa1, bf16x8& pa2, bf16x8& pa3) {
; #pragma unroll
;   for (int r = 0; r < 16; ++r) p1[r] = __builtin_amdgcn_exp2f(p1[r]);
;   float ps = 0;
; #pragma unroll
;   for (int r = 0; r < 16; ++r) ps += p0[r];
; #pragma unroll
;   for (int r = 0; r < 16; ++r) ps += p1[r];
;   { auto rr = __builtin_amdgcn_permlane32_swap(__float_as_uint(ps), __float_as_uint(ps), false, false);
;     ps = __uint_as_float(rr[0]) + __uint_as_float(rr[1]); }
;   l_reg = l_reg * alpha + ps;
;     ...
;   PK4(p0, 0, pa0); PK4(p0, 8, pa1); PK4(p1, 0, pa2); PK4(p1, 8, pa3);
;     ...
; }
; template <int DK, bool QL>
; __device__ __forceinline__ void qkt(f32x16& p0, f32x16& p1, const bf16* Ks, const bf16x8* qr, const char* ql, int r32, int hi) {
;   p0 = f32x16{}; p1 = f32x16{};
; #pragma unroll
;   for (int d0 = 0; d0 < DK / 16; ++d0) { int cb = (d0 * 16 + hi * 8) * 2;
;     const bf16x8 qv = QL ? *reinterpret_cast<const bf16x8*>(ql + d0 * 1024) : qr[d0];
;     bf16x8 b0 = *reinterpret_cast<const bf16x8*>((const char*)Ks + kswz<DK>(r32, cb));
;     bf16x8 b1 = *reinterpret_cast<const bf16x8*>((const char*)Ks + kswz<DK>(32 + r32, cb));
;     p0 = __builtin_amdgcn_mfma_f32_32x32x16_bf16(b0, qv, p0, 0, 0, 0);
;     p1 = __builtin_amdgcn_mfma_f32_32x32x16_bf16(b1, qv, p1, 0, 0, 0); }
; }
.LBB0_686:
	v_cndmask_b32_e64 v223, v138, v142, s[2:3]
	v_mul_f32_e32 v224, 0xbe38aa3b, v223
	v_fmamk_f32 v82, v82, 0x3e38aa3b, v224
	v_fmamk_f32 v83, v83, 0x3e38aa3b, v224
	v_fmamk_f32 v84, v84, 0x3e38aa3b, v224
	v_fmamk_f32 v85, v85, 0x3e38aa3b, v224
	v_fmamk_f32 v86, v86, 0x3e38aa3b, v224
	v_fmamk_f32 v87, v87, 0x3e38aa3b, v224
	v_fmamk_f32 v88, v88, 0x3e38aa3b, v224
	v_fmamk_f32 v89, v89, 0x3e38aa3b, v224
	v_fmamk_f32 v90, v90, 0x3e38aa3b, v224
	v_fmamk_f32 v91, v91, 0x3e38aa3b, v224
	v_fmamk_f32 v92, v92, 0x3e38aa3b, v224
	v_fmamk_f32 v93, v93, 0x3e38aa3b, v224
	v_fmamk_f32 v94, v94, 0x3e38aa3b, v224
	v_fmamk_f32 v95, v95, 0x3e38aa3b, v224
	v_fmamk_f32 v96, v96, 0x3e38aa3b, v224
	v_fmamk_f32 v97, v97, 0x3e38aa3b, v224
	v_exp_f32_e32 v138, v82
	v_exp_f32_e32 v153, v83
	v_exp_f32_e32 v139, v84
	v_exp_f32_e32 v152, v85
	v_exp_f32_e32 v140, v86
	v_exp_f32_e32 v151, v87
	v_exp_f32_e32 v141, v88
	v_exp_f32_e32 v150, v89
	v_exp_f32_e32 v142, v90
	v_exp_f32_e32 v149, v91
	v_exp_f32_e32 v143, v92
	v_exp_f32_e32 v148, v93
	v_exp_f32_e32 v144, v94
	v_exp_f32_e32 v147, v95
	v_exp_f32_e32 v145, v96
	v_exp_f32_e32 v146, v97
	v_fmamk_f32 v233, v66, 0x3e38aa3b, v224
	v_fmamk_f32 v234, v67, 0x3e38aa3b, v224
	v_fmamk_f32 v235, v68, 0x3e38aa3b, v224
	v_fmamk_f32 v236, v69, 0x3e38aa3b, v224
	v_fmamk_f32 v237, v70, 0x3e38aa3b, v224
	v_fmamk_f32 v226, v71, 0x3e38aa3b, v224
	v_fmamk_f32 v227, v72, 0x3e38aa3b, v224
	v_fmamk_f32 v228, v73, 0x3e38aa3b, v224
	v_fmamk_f32 v229, v74, 0x3e38aa3b, v224
	v_fmamk_f32 v230, v75, 0x3e38aa3b, v224
	v_fmamk_f32 v231, v76, 0x3e38aa3b, v224
	v_fmamk_f32 v232, v77, 0x3e38aa3b, v224
	v_fmamk_f32 v225, v78, 0x3e38aa3b, v224
	v_fmamk_f32 v238, v79, 0x3e38aa3b, v224
	v_fmamk_f32 v239, v80, 0x3e38aa3b, v224
	v_fmac_f32_e32 v224, 0x3e38aa3b, v81
	s_waitcnt lgkmcnt(0)
	s_barrier
	ds_write_b128 v214, v[114:117]
	ds_write_b128 v215, v[118:121]
	ds_read_b128 v[66:69], v212 offset:32768
	ds_read_b128 v[70:73], v212 offset:36864
	ds_read_b128 v[182:185], v217 offset:32768
	ds_read_b128 v[190:193], v217 offset:36864
	ds_read_b128 v[168:171], v218 offset:32768
	ds_read_b128 v[194:197], v218 offset:36864
	v_exp_f32_e32 v164, v233
	v_exp_f32_e32 v233, v224
	v_add_f32_e32 v224, 0, v138
	v_add_f32_e32 v224, v153, v224
	s_waitcnt lgkmcnt(5)
	v_mfma_f32_32x32x16_bf16 v[82:97], v[66:69], v[110:113], 0
	v_add_f32_e32 v224, v139, v224
	v_add_f32_e32 v224, v152, v224
	v_add_f32_e32 v224, v140, v224
	ds_read_b128 v[240:243], v216 offset:32768
	ds_read_b128 v[244:247], v216 offset:36864
	v_add_f32_e32 v224, v151, v224
	v_add_f32_e32 v224, v141, v224
	v_add_f32_e32 v224, v150, v224
	s_waitcnt lgkmcnt(6)
	v_mfma_f32_32x32x16_bf16 v[66:81], v[70:73], v[110:113], 0
	v_add_f32_e32 v224, v142, v224
	v_add_f32_e32 v224, v149, v224
	v_add_f32_e32 v224, v143, v224
	v_add_f32_e32 v224, v148, v224
	v_add_f32_e32 v224, v144, v224
	v_exp_f32_e32 v165, v234
	v_add_f32_e32 v224, v147, v224
	s_waitcnt lgkmcnt(1)
	v_mfma_f32_32x32x16_bf16 v[82:97], v[240:243], v[106:109], v[82:97]
	v_exp_f32_e32 v166, v235
	v_add_f32_e32 v224, v145, v224
	v_exp_f32_e32 v167, v236
	v_add_f32_e32 v224, v146, v224
	v_exp_f32_e32 v172, v237
	v_add_f32_e32 v224, v164, v224
	v_exp_f32_e32 v173, v226
	s_waitcnt lgkmcnt(0)
	v_mfma_f32_32x32x16_bf16 v[66:81], v[244:247], v[106:109], v[66:81]
	v_add_f32_e32 v224, v165, v224
	v_exp_f32_e32 v174, v227
	v_add_f32_e32 v224, v166, v224
	v_exp_f32_e32 v175, v228
	v_add_f32_e32 v224, v167, v224
	v_exp_f32_e32 v226, v229
	s_waitcnt lgkmcnt(0)
	v_mfma_f32_32x32x16_bf16 v[82:97], v[182:185], v[98:101], v[82:97]
	v_add_f32_e32 v224, v172, v224
	v_exp_f32_e32 v227, v230
	v_add_f32_e32 v224, v173, v224
	v_exp_f32_e32 v228, v231
	v_add_f32_e32 v224, v174, v224
	v_exp_f32_e32 v229, v232
	v_add_f32_e32 v224, v175, v224
	s_waitcnt lgkmcnt(0)
	v_mfma_f32_32x32x16_bf16 v[66:81], v[190:193], v[98:101], v[66:81]
	v_exp_f32_e32 v230, v225
	v_add_f32_e32 v224, v226, v224
	v_exp_f32_e32 v231, v238
	v_add_f32_e32 v224, v227, v224
	v_exp_f32_e32 v232, v239
	v_add_f32_e32 v224, v228, v224
	s_waitcnt lgkmcnt(0)
	v_mfma_f32_32x32x16_bf16 v[82:97], v[168:171], v[102:105], v[82:97]
	v_add_f32_e32 v224, v229, v224
	v_add_f32_e32 v224, v230, v224
	v_add_f32_e32 v224, v231, v224
	v_add_f32_e32 v224, v232, v224
	v_add_f32_e32 v224, v233, v224
	v_mov_b32_e32 v225, v224
	v_cvt_pk_bf16_f32 v138, v138, v153
	s_waitcnt lgkmcnt(0)
	v_mfma_f32_32x32x16_bf16 v[66:81], v[194:197], v[102:105], v[66:81]
	v_cvt_pk_bf16_f32 v139, v139, v152
	v_cvt_pk_bf16_f32 v140, v140, v151
	v_cvt_pk_bf16_f32 v141, v141, v150
	v_cvt_pk_bf16_f32 v142, v142, v149
	v_cvt_pk_bf16_f32 v143, v143, v148
	v_cvt_pk_bf16_f32 v144, v144, v147
	v_cvt_pk_bf16_f32 v145, v145, v146
	v_cvt_pk_bf16_f32 v146, v164, v165
	v_cvt_pk_bf16_f32 v147, v166, v167
	v_cvt_pk_bf16_f32 v148, v172, v173
	v_cvt_pk_bf16_f32 v149, v174, v175
	v_cvt_pk_bf16_f32 v150, v226, v227
	v_cvt_pk_bf16_f32 v151, v228, v229
	v_cvt_pk_bf16_f32 v152, v230, v231
	v_cvt_pk_bf16_f32 v153, v232, v233
	v_permlane32_swap_b32_e32 v224, v225
	v_permlane32_swap_b32_e32 v138, v140
	v_permlane32_swap_b32_e32 v139, v141
	v_permlane32_swap_b32_e32 v142, v144
	v_permlane32_swap_b32_e32 v143, v145
	v_permlane32_swap_b32_e32 v146, v148
	v_permlane32_swap_b32_e32 v147, v149
	v_permlane32_swap_b32_e32 v150, v152
	v_permlane32_swap_b32_e32 v151, v153
	s_cmp_gt_u32 s9, 60
	s_cselect_b64 s[4:5], -1, 0
	s_and_b64 vcc, exec, s[4:5]
	s_cbranch_vccnz .Lod_d1
	v_add_co_u32_e32 v114, vcc, 0xe180000, v160
	s_nop 1
	v_addc_co_u32_e32 v115, vcc, 0, v161, vcc
	v_add_co_u32_e32 v118, vcc, 0xe1d0000, v160
	s_nop 1
	v_addc_co_u32_e32 v119, vcc, 0, v161, vcc
	v_add_co_u32_e32 v122, vcc, 0xe180000, v176
	global_load_dwordx4 v[114:117], v[114:115], off offset:2048
	s_nop 0
	global_load_dwordx4 v[118:121], v[118:119], off offset:2048
	v_addc_co_u32_e32 v123, vcc, 0, v177, vcc
	global_load_dwordx4 v[122:125], v[122:123], off offset:1024

; #define SBAR() __builtin_amdgcn_sched_barrier(0)
; __device__ __forceinline__ void finishSM(f32x16& p0, f32x16& p1, float alpha, float& l_reg, bf16x8& pa0, bf16x8& pa1, bf16x8& pa2, bf16x8& pa3) {
; #pragma unroll
;   for (int r = 0; r < 16; ++r) p1[r] = __builtin_amdgcn_exp2f(p1[r]);
;   float ps = 0;
; #pragma unroll
;   for (int r = 0; r < 16; ++r) ps += p0[r];
; #pragma unroll
;   for (int r = 0; r < 16; ++r) ps += p1[r];
;   { auto rr = __builtin_amdgcn_permlane32_swap(__float_as_uint(ps), __float_as_uint(ps), false, false);
;     ps = __uint_as_float(rr[0]) + __uint_as_float(rr[1]); }
;   l_reg = l_reg * alpha + ps;
;     ...
;   PK4(p0, 0, pa0); PK4(p0, 8, pa1); PK4(p1, 0, pa2); PK4(p1, 8, pa3);
;     ...
; }
; template <int DK, bool QL>
; __device__ __forceinline__ void qkt(f32x16& p0, f32x16& p1, const bf16* Ks, const bf16x8* qr, const char* ql, int r32, int hi) {
;   p0 = f32x16{}; p1 = f32x16{};
; #pragma unroll
;   for (int d0 = 0; d0 < DK / 16; ++d0) { int cb = (d0 * 16 + hi * 8) * 2;
;     const bf16x8 qv = QL ? *reinterpret_cast<const bf16x8*>(ql + d0 * 1024) : qr[d0];
;     bf16x8 b0 = *reinterpret_cast<const bf16x8*>((const char*)Ks + kswz<DK>(r32, cb));
;     bf16x8 b1 = *reinterpret_cast<const bf16x8*>((const char*)Ks + kswz<DK>(32 + r32, cb));
;     p0 = __builtin_amdgcn_mfma_f32_32x32x16_bf16(b0, qv, p0, 0, 0, 0);
;     p1 = __builtin_amdgcn_mfma_f32_32x32x16_bf16(b1, qv, p1, 0, 0, 0); }
; }
; template <int OFF> __device__ __forceinline__ s16x4 tr_read(int vb) {
;   s16x4 r; asm volatile("ds_read_b64_tr_b16 %0, %1 offset:%2" : "=&v"(r) : "v"(vb), "i"(OFF) : "memory"); return r;
; }
; template <int D0> __device__ __forceinline__ void pv_one(f32x16& od, int vb, bf16x8 pa0, bf16x8 pa1, bf16x8 pa2, bf16x8 pa3) {
;   const s16x4 l0 = tr_read<v_rd_off(D0, 0, 0)>(vb), h0 = tr_read<v_rd_off(D0, 0, 1)>(vb), l1 = tr_read<v_rd_off(D0, 1, 0)>(vb), h1 = tr_read<v_rd_off(D0, 1, 1)>(vb);
;   const s16x4 l2 = tr_read<v_rd_off(D0, 2, 0)>(vb), h2 = tr_read<v_rd_off(D0, 2, 1)>(vb), l3 = tr_read<v_rd_off(D0, 3, 0)>(vb), h3 = tr_read<v_rd_off(D0, 3, 1)>(vb);
;   asm volatile("s_waitcnt lgkmcnt(0)" ::: "memory"); SBAR();
;     ...
;   od = __builtin_amdgcn_mfma_f32_32x32x16_bf16(pa0, PK(l0, h0), od, 0, 0, 0);
;   od = __builtin_amdgcn_mfma_f32_32x32x16_bf16(pa1, PK(l1, h1), od, 0, 0, 0);
;   od = __builtin_amdgcn_mfma_f32_32x32x16_bf16(pa2, PK(l2, h2), od, 0, 0, 0);
.LBB0_701:
	ds_read_b128 v[66:69], v215 offset:49152
	ds_read_b128 v[70:73], v215 offset:53248
	ds_read_b128 v[182:185], v217 offset:49152
	ds_read_b128 v[190:193], v217 offset:53248
	ds_read_b128 v[168:171], v218 offset:49152
	ds_read_b128 v[194:197], v218 offset:53248
	v_exp_f32_e32 v143, v138
	v_add_f32_e32 v138, 0, v177
	v_add_f32_e32 v138, v226, v138
	s_waitcnt lgkmcnt(5)
	v_mfma_f32_32x32x16_bf16 v[82:97], v[66:69], v[110:113], 0
	v_add_f32_e32 v138, v161, v138
	v_add_f32_e32 v138, v223, v138
	v_add_f32_e32 v138, v153, v138
	ds_read_b128 v[228:231], v216 offset:49152
	ds_read_b128 v[232:235], v216 offset:53248
	v_add_f32_e32 v138, v176, v138
	v_add_f32_e32 v138, v152, v138
	v_add_f32_e32 v138, v160, v138
	s_waitcnt lgkmcnt(6)
	v_mfma_f32_32x32x16_bf16 v[66:81], v[70:73], v[110:113], 0
	v_add_f32_e32 v138, v149, v138
	v_add_f32_e32 v138, v151, v138
	v_add_f32_e32 v138, v147, v138
	v_add_f32_e32 v138, v150, v138
	v_add_f32_e32 v138, v145, v138
	v_exp_f32_e32 v164, v139
	v_add_f32_e32 v138, v148, v138
	s_waitcnt lgkmcnt(1)
	v_mfma_f32_32x32x16_bf16 v[82:97], v[228:231], v[106:109], v[82:97]
	v_exp_f32_e32 v136, v136
	v_add_f32_e32 v138, v144, v138
	v_exp_f32_e32 v137, v137
	v_add_f32_e32 v138, v146, v138
	v_exp_f32_e32 v130, v130
	v_add_f32_e32 v138, v143, v138
	v_exp_f32_e32 v131, v131
	s_waitcnt lgkmcnt(0)
	v_mfma_f32_32x32x16_bf16 v[66:81], v[232:235], v[106:109], v[66:81]
	v_add_f32_e32 v138, v164, v138
	v_exp_f32_e32 v128, v128
	v_add_f32_e32 v138, v136, v138
	v_exp_f32_e32 v129, v129
	v_add_f32_e32 v138, v137, v138
	v_exp_f32_e32 v126, v126
	s_waitcnt lgkmcnt(0)
	v_mfma_f32_32x32x16_bf16 v[82:97], v[182:185], v[102:105], v[82:97]
	v_add_f32_e32 v138, v130, v138
	v_exp_f32_e32 v127, v127
	v_add_f32_e32 v138, v131, v138
	v_exp_f32_e32 v165, v140
	v_add_f32_e32 v138, v128, v138
	v_exp_f32_e32 v166, v141
	v_add_f32_e32 v138, v129, v138
	s_waitcnt lgkmcnt(0)
	v_mfma_f32_32x32x16_bf16 v[66:81], v[190:193], v[102:105], v[66:81]
	v_exp_f32_e32 v134, v134
	v_add_f32_e32 v138, v126, v138
	v_exp_f32_e32 v135, v135
	v_add_f32_e32 v138, v127, v138
	v_exp_f32_e32 v132, v132
	v_add_f32_e32 v138, v165, v138
	s_waitcnt lgkmcnt(0)
	v_mfma_f32_32x32x16_bf16 v[82:97], v[168:171], v[98:101], v[82:97]
	v_exp_f32_e32 v133, v133
	v_add_f32_e32 v138, v166, v138
	v_add_f32_e32 v138, v134, v138
	v_add_f32_e32 v138, v135, v138
	v_add_f32_e32 v138, v132, v138
	v_add_f32_e32 v220, v133, v138
	v_mov_b32_e32 v221, v220
	s_waitcnt lgkmcnt(0)
	v_mfma_f32_32x32x16_bf16 v[66:81], v[194:197], v[98:101], v[66:81]
	v_cvt_pk_bf16_f32 v138, v177, v226
	v_cvt_pk_bf16_f32 v139, v161, v223
	v_cvt_pk_bf16_f32 v140, v153, v176
	v_cvt_pk_bf16_f32 v141, v152, v160
	v_cvt_pk_bf16_f32 v222, v149, v151
	v_cvt_pk_bf16_f32 v223, v147, v150
	v_cvt_pk_bf16_f32 v224, v145, v148
	v_permlane32_swap_b32_e32 v220, v221
	v_permlane32_swap_b32_e32 v138, v140
	v_cvt_pk_bf16_f32 v225, v144, v146
	v_permlane32_swap_b32_e32 v222, v224
	v_cvt_pk_bf16_f32 v144, v143, v164
	v_cvt_pk_bf16_f32 v145, v136, v137
	v_cvt_pk_bf16_f32 v146, v130, v131
	v_cvt_pk_bf16_f32 v147, v128, v129
	v_cvt_pk_bf16_f32 v148, v126, v127
	v_cvt_pk_bf16_f32 v149, v165, v166
	v_cvt_pk_bf16_f32 v150, v134, v135
	v_cvt_pk_bf16_f32 v151, v132, v133
	v_permlane32_swap_b32_e32 v139, v141
	v_permlane32_swap_b32_e32 v223, v225
	v_permlane32_swap_b32_e32 v144, v146
	v_permlane32_swap_b32_e32 v145, v147
	v_permlane32_swap_b32_e32 v148, v150
	v_permlane32_swap_b32_e32 v149, v151
	v_readlane_b32 s2, v254, 32
	v_readlane_b32 s3, v254, 33
	s_mov_b32 s4, 0xe0e0000
	s_mov_b32 s5, 0xe130000
	v_lshl_add_u64 v[160:161], v[156:157], 0, s[2:3]
	v_add_co_u32_e32 v126, vcc, s4, v160
	v_lshl_add_u64 v[176:177], v[158:159], 0, s[2:3]
	s_nop 0
	v_addc_co_u32_e32 v127, vcc, 0, v161, vcc
	v_add_co_u32_e32 v130, vcc, s5, v160
	s_nop 1
	v_addc_co_u32_e32 v131, vcc, 0, v161, vcc
	v_add_co_u32_e32 v134, vcc, s4, v176
	global_load_dwordx4 v[126:129], v[126:127], off offset:2048
	s_nop 0
	global_load_dwordx4 v[130:133], v[130:131], off offset:2048
	v_addc_co_u32_e32 v135, vcc, 0, v177, vcc
	global_load_dwordx4 v[134:137], v[134:135], off offset:1152
	ds_read_b64_tr_b16 v[226:227], v211 offset:0
	ds_read_b64_tr_b16 v[228:229], v211 offset:0x800
	ds_read_b64_tr_b16 v[230:231], v211 offset:0x1000
	ds_read_b64_tr_b16 v[232:233], v211 offset:0x1800
	ds_read_b64_tr_b16 v[234:235], v211 offset:0x2000
	ds_read_b64_tr_b16 v[236:237], v211 offset:0x2800
	ds_read_b64_tr_b16 v[238:239], v211 offset:0x3000
	ds_read_b64_tr_b16 v[240:241], v211 offset:0x3800
	s_waitcnt lgkmcnt(6)
	s_nop 0
	v_mfma_f32_32x32x16_bf16 v[2:17], v[138:141], v[226:229], v[2:17]
	ds_read_b64_tr_b16 v[226:227], v211 offset:0x200
	ds_read_b64_tr_b16 v[228:229], v211 offset:0xa00
	s_waitcnt lgkmcnt(6)
	v_mfma_f32_32x32x16_bf16 v[2:17], v[222:225], v[230:233], v[2:17]
	ds_read_b64_tr_b16 v[230:231], v211 offset:0x1200
	ds_read_b64_tr_b16 v[232:233], v211 offset:0x1a00
	s_waitcnt lgkmcnt(6)
	v_mfma_f32_32x32x16_bf16 v[2:17], v[144:147], v[234:237], v[2:17]
	ds_read_b64_tr_b16 v[234:235], v211 offset:0x2200
	ds_read_b64_tr_b16 v[236:237], v211 offset:0x2a00
	s_waitcnt lgkmcnt(6)
	v_mfma_f32_32x32x16_bf16 v[2:17], v[148:151], v[238:241], v[2:17]
	ds_read_b64_tr_b16 v[238:239], v211 offset:0x3200
	ds_read_b64_tr_b16 v[240:241], v211 offset:0x3a00
	s_waitcnt lgkmcnt(6)
	v_mfma_f32_32x32x16_bf16 v[50:65], v[138:141], v[226:229], v[50:65]
	ds_read_b64_tr_b16 v[226:227], v211 offset:0x400
	ds_read_b64_tr_b16 v[228:229], v211 offset:0xc00
	s_waitcnt lgkmcnt(6)
	v_mfma_f32_32x32x16_bf16 v[50:65], v[222:225], v[230:233], v[50:65]
	ds_read_b64_tr_b16 v[230:231], v211 offset:0x1400
	ds_read_b64_tr_b16 v[232:233], v211 offset:0x1c00
	s_waitcnt lgkmcnt(6)
; #define SBAR() __builtin_amdgcn_sched_barrier(0)
; __device__ __forceinline__ void partialSM(f32x16& p0, f32x16& p1, float& m_reg, float& mn, float& alpha, float C, float thrRaw) {
;   float pmax = p0[0];
; #pragma unroll
;   for (int r = 1; r < 16; ++r) pmax = fmaxf(pmax, p0[r]);
; #pragma unroll
;   for (int r = 0; r < 16; ++r) pmax = fmaxf(pmax, p1[r]);
;   { auto rr = __builtin_amdgcn_permlane32_swap(__float_as_uint(pmax), __float_as_uint(pmax), false, false);
;     pmax = fmaxf(__uint_as_float(rr[0]), __uint_as_float(rr[1])); }
;   if (__builtin_expect(__all(pmax - m_reg <= thrRaw), 1)) { mn = m_reg; alpha = 1.f; }
;   else { mn = fmaxf(m_reg, pmax); alpha = __builtin_amdgcn_exp2f((m_reg - mn) * C); m_reg = mn; }
;   float mnC = -mn * C;
; #pragma unroll
;   for (int r = 0; r < 16; ++r) p0[r] = fmaf(p0[r], C, mnC);
; #pragma unroll
;   for (int r = 0; r < 16; ++r) p1[r] = fmaf(p1[r], C, mnC);
; #pragma unroll
;   for (int r = 0; r < 16; ++r) p0[r] = __builtin_amdgcn_exp2f(p0[r]);
; }
; template <int OFF> __device__ __forceinline__ s16x4 tr_read(int vb) {
;   s16x4 r; asm volatile("ds_read_b64_tr_b16 %0, %1 offset:%2" : "=&v"(r) : "v"(vb), "i"(OFF) : "memory"); return r;
; }
; template <int D0> __device__ __forceinline__ void pv_one(f32x16& od, int vb, bf16x8 pa0, bf16x8 pa1, bf16x8 pa2, bf16x8 pa3) {
;   const s16x4 l0 = tr_read<v_rd_off(D0, 0, 0)>(vb), h0 = tr_read<v_rd_off(D0, 0, 1)>(vb), l1 = tr_read<v_rd_off(D0, 1, 0)>(vb), h1 = tr_read<v_rd_off(D0, 1, 1)>(vb);
;   const s16x4 l2 = tr_read<v_rd_off(D0, 2, 0)>(vb), h2 = tr_read<v_rd_off(D0, 2, 1)>(vb), l3 = tr_read<v_rd_off(D0, 3, 0)>(vb), h3 = tr_read<v_rd_off(D0, 3, 1)>(vb);
;   asm volatile("s_waitcnt lgkmcnt(0)" ::: "memory"); SBAR();
;     ...
;   od = __builtin_amdgcn_mfma_f32_32x32x16_bf16(pa0, PK(l0, h0), od, 0, 0, 0);
;   od = __builtin_amdgcn_mfma_f32_32x32x16_bf16(pa1, PK(l1, h1), od, 0, 0, 0);
;   od = __builtin_amdgcn_mfma_f32_32x32x16_bf16(pa2, PK(l2, h2), od, 0, 0, 0);
;   od = __builtin_amdgcn_mfma_f32_32x32x16_bf16(pa3, PK(l3, h3), od, 0, 0, 0);
;     ...
; }
; __device__ __forceinline__ void pv_d0(f32x16* o, int vb, bf16x8 pa0, bf16x8 pa1, bf16x8 pa2, bf16x8 pa3) {
;   pv_one<0>(o[0], vb, pa0, pa1, pa2, pa3); pv_one<1>(o[1], vb, pa0, pa1, pa2, pa3); pv_one<2>(o[2], vb, pa0, pa1, pa2, pa3); pv_one<3>(o[3], vb, pa0, pa1, pa2, pa3);
	v_mfma_f32_32x32x16_bf16 v[50:65], v[144:147], v[234:237], v[50:65]
	ds_read_b64_tr_b16 v[234:235], v211 offset:0x2400
	ds_read_b64_tr_b16 v[236:237], v211 offset:0x2c00
	s_waitcnt lgkmcnt(6)
	v_mfma_f32_32x32x16_bf16 v[50:65], v[148:151], v[238:241], v[50:65]
	ds_read_b64_tr_b16 v[238:239], v211 offset:0x3400
	ds_read_b64_tr_b16 v[240:241], v211 offset:0x3c00
	s_waitcnt lgkmcnt(6)
	v_mfma_f32_32x32x16_bf16 v[34:49], v[138:141], v[226:229], v[34:49]
	ds_read_b64_tr_b16 v[226:227], v211 offset:0x600
	ds_read_b64_tr_b16 v[228:229], v211 offset:0xe00
	s_waitcnt lgkmcnt(6)
	v_mfma_f32_32x32x16_bf16 v[34:49], v[222:225], v[230:233], v[34:49]
	ds_read_b64_tr_b16 v[230:231], v211 offset:0x1600
	ds_read_b64_tr_b16 v[232:233], v211 offset:0x1e00
	s_waitcnt lgkmcnt(6)
	v_mfma_f32_32x32x16_bf16 v[34:49], v[144:147], v[234:237], v[34:49]
	ds_read_b64_tr_b16 v[234:235], v211 offset:0x2600
	ds_read_b64_tr_b16 v[236:237], v211 offset:0x2e00
	s_waitcnt lgkmcnt(6)
	v_mfma_f32_32x32x16_bf16 v[34:49], v[148:151], v[238:241], v[34:49]
	ds_read_b64_tr_b16 v[238:239], v211 offset:0x3600
	ds_read_b64_tr_b16 v[240:241], v211 offset:0x3e00
	s_waitcnt lgkmcnt(6)
	v_mfma_f32_32x32x16_bf16 v[18:33], v[138:141], v[226:229], v[18:33]
	v_max_f32_e32 v138, v83, v83
	v_max_f32_e32 v139, v82, v82
	v_max_f32_e32 v138, v139, v138
	v_max3_f32 v138, v138, v84, v85
	v_max3_f32 v138, v138, v86, v87
	v_max3_f32 v138, v138, v88, v89
	v_max3_f32 v138, v138, v90, v91
	v_max3_f32 v138, v138, v92, v93
	v_max3_f32 v138, v138, v94, v95
	s_waitcnt lgkmcnt(4)
	v_mfma_f32_32x32x16_bf16 v[18:33], v[222:225], v[230:233], v[18:33]
	v_max3_f32 v138, v138, v96, v97
	v_max3_f32 v138, v138, v66, v67
	v_max3_f32 v138, v138, v68, v69
	v_max3_f32 v138, v138, v70, v71
	v_max3_f32 v138, v138, v72, v73
	v_max3_f32 v138, v138, v74, v75
	v_max3_f32 v138, v138, v76, v77
	v_max3_f32 v138, v138, v78, v79
	s_waitcnt lgkmcnt(2)
	v_mfma_f32_32x32x16_bf16 v[18:33], v[144:147], v[234:237], v[18:33]
	v_max3_f32 v138, v138, v80, v81
	v_mov_b32_e32 v139, v138
	s_nop 1
	v_permlane32_swap_b32_e32 v138, v139
	v_max_f32_e32 v139, v139, v139
	v_max_f32_e32 v138, v138, v138
	v_max_f32_e32 v138, v138, v139
	v_sub_f32_e32 v139, v138, v142
	s_mov_b32 s2, 0x42800000
	v_cmp_ge_f32_e32 vcc, s2, v139
	v_max_f32_e32 v139, v142, v142
	v_max_f32_e32 v138, v139, v138
	s_waitcnt lgkmcnt(0)
	v_mfma_f32_32x32x16_bf16 v[18:33], v[148:151], v[238:241], v[18:33]
	v_sub_f32_e32 v139, v142, v138
	v_mul_f32_e32 v139, 0x3e38aa3b, v139
	v_exp_f32_e32 v139, v139
	s_cmp_eq_u64 vcc, exec
	s_cselect_b64 s[2:3], -1, 0
	s_waitcnt vmcnt(3)
	v_cndmask_b32_e64 v222, v139, 1.0, s[2:3]
	v_cmp_gt_f32_e32 vcc, 1.0, v222
	s_waitcnt vmcnt(3)
	ds_write_b128 v214, v[122:125] offset:32768
	s_cbranch_vccz .LBB0_705
	s_and_saveexec_b64 s[4:5], s[0:1]
	ds_write_b32 v208, v222 offset:128
	s_or_b64 exec, exec, s[4:5]
	s_waitcnt lgkmcnt(0)
	v_add_u32_e32 v139, v207, v0
	ds_read_b128 v[144:147], v139 offset:224
	ds_read_b128 v[148:151], v139 offset:192
	ds_read_b128 v[224:227], v139 offset:160
	ds_read_b128 v[228:231], v139 offset:128
	s_waitcnt lgkmcnt(3)
	v_pk_mul_f32 v[14:15], v[14:15], v[144:145]
	s_waitcnt lgkmcnt(2)
	v_pk_mul_f32 v[10:11], v[10:11], v[148:149]
	s_waitcnt lgkmcnt(1)
	v_pk_mul_f32 v[6:7], v[6:7], v[224:225]
	v_pk_mul_f32 v[16:17], v[16:17], v[146:147]
	v_pk_mul_f32 v[12:13], v[12:13], v[150:151]
	v_pk_mul_f32 v[8:9], v[8:9], v[226:227]
	s_waitcnt lgkmcnt(0)
	v_pk_mul_f32 v[4:5], v[4:5], v[230:231]
	v_pk_mul_f32 v[2:3], v[2:3], v[228:229]
	v_pk_mul_f32 v[62:63], v[144:145], v[62:63]
	v_pk_mul_f32 v[58:59], v[148:149], v[58:59]
	v_pk_mul_f32 v[54:55], v[224:225], v[54:55]
	v_pk_mul_f32 v[64:65], v[146:147], v[64:65]
	v_pk_mul_f32 v[60:61], v[150:151], v[60:61]
	v_pk_mul_f32 v[56:57], v[226:227], v[56:57]
	v_pk_mul_f32 v[52:53], v[230:231], v[52:53]
	v_pk_mul_f32 v[50:51], v[228:229], v[50:51]
	v_pk_mul_f32 v[46:47], v[144:145], v[46:47]
	v_pk_mul_f32 v[42:43], v[148:149], v[42:43]
	v_pk_mul_f32 v[38:39], v[224:225], v[38:39]
	v_pk_mul_f32 v[48:49], v[146:147], v[48:49]
	v_pk_mul_f32 v[44:45], v[150:151], v[44:45]
	v_pk_mul_f32 v[40:41], v[226:227], v[40:41]
	v_pk_mul_f32 v[36:37], v[230:231], v[36:37]
	v_pk_mul_f32 v[34:35], v[228:229], v[34:35]
	v_pk_mul_f32 v[30:31], v[144:145], v[30:31]
	v_pk_mul_f32 v[26:27], v[148:149], v[26:27]
	v_pk_mul_f32 v[22:23], v[224:225], v[22:23]
	v_pk_mul_f32 v[32:33], v[146:147], v[32:33]
	v_pk_mul_f32 v[28:29], v[150:151], v[28:29]
	v_pk_mul_f32 v[24:25], v[226:227], v[24:25]
	v_pk_mul_f32 v[20:21], v[230:231], v[20:21]
	v_pk_mul_f32 v[18:19], v[228:229], v[18:19]
; __device__ __forceinline__ void partialSM(f32x16& p0, f32x16& p1, float& m_reg, float& mn, float& alpha, float C, float thrRaw) {
;     ...
;   float mnC = -mn * C;
; #pragma unroll
;   for (int r = 0; r < 16; ++r) p0[r] = fmaf(p0[r], C, mnC);
; #pragma unroll
;   for (int r = 0; r < 16; ++r) p1[r] = fmaf(p1[r], C, mnC);
; #pragma unroll
;   for (int r = 0; r < 16; ++r) p0[r] = __builtin_amdgcn_exp2f(p0[r]);
; }
; __device__ __forceinline__ void finishSM(f32x16& p0, f32x16& p1, float alpha, float& l_reg, bf16x8& pa0, bf16x8& pa1, bf16x8& pa2, bf16x8& pa3) {
; #pragma unroll
;   for (int r = 0; r < 16; ++r) p1[r] = __builtin_amdgcn_exp2f(p1[r]);
;   float ps = 0;
; #pragma unroll
;   for (int r = 0; r < 16; ++r) ps += p0[r];
; #pragma unroll
;   for (int r = 0; r < 16; ++r) ps += p1[r];
;   { auto rr = __builtin_amdgcn_permlane32_swap(__float_as_uint(ps), __float_as_uint(ps), false, false);
;     ps = __uint_as_float(rr[0]) + __uint_as_float(rr[1]); }
;   l_reg = l_reg * alpha + ps;
;     ...
;   PK4(p0, 0, pa0); PK4(p0, 8, pa1); PK4(p1, 0, pa2); PK4(p1, 8, pa3);
;     ...
; }
; template <int DK, bool QL>
; __device__ __forceinline__ void qkt(f32x16& p0, f32x16& p1, const bf16* Ks, const bf16x8* qr, const char* ql, int r32, int hi) {
;   p0 = f32x16{}; p1 = f32x16{};
; #pragma unroll
;   for (int d0 = 0; d0 < DK / 16; ++d0) { int cb = (d0 * 16 + hi * 8) * 2;
;     const bf16x8 qv = QL ? *reinterpret_cast<const bf16x8*>(ql + d0 * 1024) : qr[d0];
;     bf16x8 b0 = *reinterpret_cast<const bf16x8*>((const char*)Ks + kswz<DK>(r32, cb));
;     bf16x8 b1 = *reinterpret_cast<const bf16x8*>((const char*)Ks + kswz<DK>(32 + r32, cb));
;     p0 = __builtin_amdgcn_mfma_f32_32x32x16_bf16(b0, qv, p0, 0, 0, 0);
;     p1 = __builtin_amdgcn_mfma_f32_32x32x16_bf16(b1, qv, p1, 0, 0, 0); }
; }
.LBB0_705:
	v_cndmask_b32_e64 v223, v138, v142, s[2:3]
	v_mul_f32_e32 v224, 0xbe38aa3b, v223
	v_fmamk_f32 v82, v82, 0x3e38aa3b, v224
	v_fmamk_f32 v83, v83, 0x3e38aa3b, v224
	v_fmamk_f32 v84, v84, 0x3e38aa3b, v224
	v_fmamk_f32 v85, v85, 0x3e38aa3b, v224
	v_fmamk_f32 v86, v86, 0x3e38aa3b, v224
	v_fmamk_f32 v87, v87, 0x3e38aa3b, v224
	v_fmamk_f32 v88, v88, 0x3e38aa3b, v224
	v_fmamk_f32 v89, v89, 0x3e38aa3b, v224
	v_fmamk_f32 v90, v90, 0x3e38aa3b, v224
	v_fmamk_f32 v91, v91, 0x3e38aa3b, v224
	v_fmamk_f32 v92, v92, 0x3e38aa3b, v224
	v_fmamk_f32 v93, v93, 0x3e38aa3b, v224
	v_fmamk_f32 v94, v94, 0x3e38aa3b, v224
	v_fmamk_f32 v95, v95, 0x3e38aa3b, v224
	v_fmamk_f32 v96, v96, 0x3e38aa3b, v224
	v_fmamk_f32 v97, v97, 0x3e38aa3b, v224
	v_exp_f32_e32 v138, v82
	v_exp_f32_e32 v153, v83
	v_exp_f32_e32 v139, v84
	v_exp_f32_e32 v152, v85
	v_exp_f32_e32 v140, v86
	v_exp_f32_e32 v151, v87
	v_exp_f32_e32 v141, v88
	v_exp_f32_e32 v150, v89
	v_exp_f32_e32 v142, v90
	v_exp_f32_e32 v149, v91
	v_exp_f32_e32 v143, v92
	v_exp_f32_e32 v148, v93
	v_exp_f32_e32 v144, v94
	v_exp_f32_e32 v147, v95
	v_exp_f32_e32 v145, v96
	v_exp_f32_e32 v146, v97
	v_fmamk_f32 v233, v66, 0x3e38aa3b, v224
	v_fmamk_f32 v234, v67, 0x3e38aa3b, v224
	v_fmamk_f32 v235, v68, 0x3e38aa3b, v224
	v_fmamk_f32 v236, v69, 0x3e38aa3b, v224
	v_fmamk_f32 v237, v70, 0x3e38aa3b, v224
	v_fmamk_f32 v226, v71, 0x3e38aa3b, v224
	v_fmamk_f32 v227, v72, 0x3e38aa3b, v224
	v_fmamk_f32 v228, v73, 0x3e38aa3b, v224
	v_fmamk_f32 v229, v74, 0x3e38aa3b, v224
	v_fmamk_f32 v230, v75, 0x3e38aa3b, v224
	v_fmamk_f32 v231, v76, 0x3e38aa3b, v224
	v_fmamk_f32 v232, v77, 0x3e38aa3b, v224
	v_fmamk_f32 v225, v78, 0x3e38aa3b, v224
	v_fmamk_f32 v238, v79, 0x3e38aa3b, v224
	v_fmamk_f32 v239, v80, 0x3e38aa3b, v224
	v_fmac_f32_e32 v224, 0x3e38aa3b, v81
	s_waitcnt lgkmcnt(0)
	s_barrier
	ds_write_b128 v212, v[114:117]
	ds_write_b128 v213, v[118:121]
	ds_read_b128 v[66:69], v215 offset:32768
	ds_read_b128 v[70:73], v215 offset:36864
	ds_read_b128 v[182:185], v217 offset:32768
	ds_read_b128 v[190:193], v217 offset:36864
	ds_read_b128 v[168:171], v218 offset:32768
	ds_read_b128 v[194:197], v218 offset:36864
	v_exp_f32_e32 v164, v233
	v_exp_f32_e32 v233, v224
	v_add_f32_e32 v224, 0, v138
	v_add_f32_e32 v224, v153, v224
	s_waitcnt lgkmcnt(5)
	v_mfma_f32_32x32x16_bf16 v[82:97], v[66:69], v[110:113], 0
	v_add_f32_e32 v224, v139, v224
	v_add_f32_e32 v224, v152, v224
	v_add_f32_e32 v224, v140, v224
	ds_read_b128 v[240:243], v216 offset:32768
	ds_read_b128 v[244:247], v216 offset:36864
	v_add_f32_e32 v224, v151, v224
	v_add_f32_e32 v224, v141, v224
	v_add_f32_e32 v224, v150, v224
	s_waitcnt lgkmcnt(6)
	v_mfma_f32_32x32x16_bf16 v[66:81], v[70:73], v[110:113], 0
	v_add_f32_e32 v224, v142, v224
	v_add_f32_e32 v224, v149, v224
	v_add_f32_e32 v224, v143, v224
	v_add_f32_e32 v224, v148, v224
	v_add_f32_e32 v224, v144, v224
	v_exp_f32_e32 v165, v234
	v_add_f32_e32 v224, v147, v224
	s_waitcnt lgkmcnt(1)
	v_mfma_f32_32x32x16_bf16 v[82:97], v[240:243], v[106:109], v[82:97]
	v_exp_f32_e32 v166, v235
	v_add_f32_e32 v224, v145, v224
	v_exp_f32_e32 v167, v236
	v_add_f32_e32 v224, v146, v224
	v_exp_f32_e32 v172, v237
	v_add_f32_e32 v224, v164, v224
	v_exp_f32_e32 v173, v226
	s_waitcnt lgkmcnt(0)
	v_mfma_f32_32x32x16_bf16 v[66:81], v[244:247], v[106:109], v[66:81]
	v_add_f32_e32 v224, v165, v224
	v_exp_f32_e32 v174, v227
	v_add_f32_e32 v224, v166, v224
	v_exp_f32_e32 v175, v228
	v_add_f32_e32 v224, v167, v224
	v_exp_f32_e32 v226, v229
	s_waitcnt lgkmcnt(0)
	v_mfma_f32_32x32x16_bf16 v[82:97], v[182:185], v[102:105], v[82:97]
	v_add_f32_e32 v224, v172, v224
	v_exp_f32_e32 v227, v230
	v_add_f32_e32 v224, v173, v224
	v_exp_f32_e32 v228, v231
	v_add_f32_e32 v224, v174, v224
	v_exp_f32_e32 v229, v232
	v_add_f32_e32 v224, v175, v224
	s_waitcnt lgkmcnt(0)
	v_mfma_f32_32x32x16_bf16 v[66:81], v[190:193], v[102:105], v[66:81]
	v_exp_f32_e32 v230, v225
	v_add_f32_e32 v224, v226, v224
	v_exp_f32_e32 v231, v238
	v_add_f32_e32 v224, v227, v224
	v_exp_f32_e32 v232, v239
	v_add_f32_e32 v224, v228, v224
	s_waitcnt lgkmcnt(0)
	v_mfma_f32_32x32x16_bf16 v[82:97], v[168:171], v[98:101], v[82:97]
	v_add_f32_e32 v224, v229, v224
	v_add_f32_e32 v224, v230, v224
	v_add_f32_e32 v224, v231, v224
	v_add_f32_e32 v224, v232, v224
	v_add_f32_e32 v224, v233, v224
	v_mov_b32_e32 v225, v224
	v_cvt_pk_bf16_f32 v138, v138, v153
	s_waitcnt lgkmcnt(0)
	v_mfma_f32_32x32x16_bf16 v[66:81], v[194:197], v[98:101], v[66:81]
	v_cvt_pk_bf16_f32 v139, v139, v152
	v_cvt_pk_bf16_f32 v140, v140, v151
	v_cvt_pk_bf16_f32 v141, v141, v150
	v_cvt_pk_bf16_f32 v142, v142, v149
	v_cvt_pk_bf16_f32 v143, v143, v148
	v_cvt_pk_bf16_f32 v144, v144, v147
	v_cvt_pk_bf16_f32 v145, v145, v146
	v_cvt_pk_bf16_f32 v146, v164, v165
	v_cvt_pk_bf16_f32 v147, v166, v167
	v_cvt_pk_bf16_f32 v148, v172, v173
	v_cvt_pk_bf16_f32 v149, v174, v175
	v_cvt_pk_bf16_f32 v150, v226, v227
	v_cvt_pk_bf16_f32 v151, v228, v229
	v_cvt_pk_bf16_f32 v152, v230, v231
	v_cvt_pk_bf16_f32 v153, v232, v233
	v_permlane32_swap_b32_e32 v224, v225
	v_permlane32_swap_b32_e32 v138, v140
	v_permlane32_swap_b32_e32 v139, v141
	v_permlane32_swap_b32_e32 v142, v144
	v_permlane32_swap_b32_e32 v143, v145
	v_permlane32_swap_b32_e32 v146, v148
	v_permlane32_swap_b32_e32 v147, v149
	v_permlane32_swap_b32_e32 v150, v152
	v_permlane32_swap_b32_e32 v151, v153
	s_cmp_gt_u32 s8, 60
	s_cselect_b64 s[4:5], -1, 0
	s_and_b64 vcc, exec, s[4:5]
	s_cbranch_vccnz .Lod_d2
	v_add_co_u32_e32 v114, vcc, 0xe180000, v160
	s_nop 1
	v_addc_co_u32_e32 v115, vcc, 0, v161, vcc
	v_add_co_u32_e32 v118, vcc, 0xe1d0000, v160
	s_nop 1
	v_addc_co_u32_e32 v119, vcc, 0, v161, vcc
	v_add_co_u32_e32 v122, vcc, 0xe180000, v176
	global_load_dwordx4 v[114:117], v[114:115], off offset:2048
	s_nop 0
	global_load_dwordx4 v[118:121], v[118:119], off offset:2048
	v_addc_co_u32_e32 v123, vcc, 0, v177, vcc
	global_load_dwordx4 v[122:125], v[122:123], off offset:1152
